# resid epilogue: second store of each piece issued after the next piece's decode; low-nibble taken from y+0x8800 (8 fewer adds per piece)
# baseline (speedup 1.0000x reference)
.LBB0_244:
	v_lshl_add_u32 v153, s38, 8, v131
	v_lshl_or_b32 v154, s22, 8, v171
	s_lshl_b32 s8, s38, 2
	s_add_i32 s8, s8, s22
	s_ashr_i32 s9, s8, 31
	s_lshl_b64 s[8:9], s[8:9], 15
	v_lshl_add_u64 v[148:149], v[142:143], 0, s[8:9]
	s_lshl_b32 s10, s22, 4
	s_lshl_b32 s11, s12, 2
	s_add_i32 s10, s10, s11
	v_and_b32_e32 v155, 24, v171
	v_lshl_add_u32 v155, v155, 1, v153
	v_lshl_add_u32 v152, v155, 6, s10
	s_mov_b32 s39, 0x7060302
	s_movk_i32 s40, 0xf0
	s_mov_b32 s24, 0xffff0000
	s_mov_b32 s25, 0xffff0000
	v_lshlrev_b32_e32 v156, 11, v153
	v_lshl_add_u32 v150, v154, 1, v156
	s_and_b64 vcc, exec, s[20:21]
	s_cbranch_vccnz .Lres_out
	v_mov_b32_e32 v151, v150
	global_load_dwordx4 v[174:177], v150, s[34:35] offset:0
	global_load_dword v222, v[148:149], off offset:0
	global_load_dwordx4 v[178:181], v150, s[34:35] offset:256
	v_add_u32_e32 v150, 0x8000, v150
	global_load_dword v223, v[148:149], off offset:256
	global_load_dwordx4 v[182:185], v150, s[34:35] offset:0
	global_load_dword v224, v[148:149], off offset:512
	global_load_dwordx4 v[186:189], v150, s[34:35] offset:256
	v_add_u32_e32 v150, 0x8000, v150
	global_load_dword v225, v[148:149], off offset:768
	global_load_dwordx4 v[190:193], v150, s[34:35] offset:0
	global_load_dword v226, v[148:149], off offset:1024
	global_load_dwordx4 v[194:197], v150, s[34:35] offset:256
	v_add_u32_e32 v150, 0x8000, v150
	global_load_dword v227, v[148:149], off offset:1280
	global_load_dwordx4 v[198:201], v150, s[34:35] offset:0
	global_load_dword v228, v[148:149], off offset:1536
	global_load_dwordx4 v[202:205], v150, s[34:35] offset:256
	v_add_u32_e32 v150, 0x28000, v150
	global_load_dword v229, v[148:149], off offset:1792
	global_load_dwordx4 v[206:209], v150, s[34:35] offset:0
	global_load_dword v230, v[148:149], off offset:2048
	global_load_dwordx4 v[210:213], v150, s[34:35] offset:256
	v_add_u32_e32 v150, 0x8000, v150
	global_load_dword v231, v[148:149], off offset:2304
	global_load_dwordx4 v[214:217], v150, s[34:35] offset:0
	global_load_dword v232, v[148:149], off offset:2560
	global_load_dwordx4 v[218:221], v150, s[34:35] offset:256
	v_add_u32_e32 v150, 0x8000, v150
	global_load_dword v233, v[148:149], off offset:2816
	global_load_dword v234, v[148:149], off offset:3072
	global_load_dword v235, v[148:149], off offset:3328
	global_load_dword v236, v[148:149], off offset:3584
	global_load_dword v237, v[148:149], off offset:3840
	s_waitcnt vmcnt(26)
	v_lshlrev_b32_e32 v153, 16, v174
	v_bfe_i32 v154, v222, 0, 4
	v_and_b32_e32 v155, 0xffff0000, v174
	v_bfe_i32 v156, v222, 4, 4
	v_lshl_add_u32 v153, v154, 12, v153
	v_lshl_add_u32 v155, v156, 12, v155
	v_fma_f32 v124, v124, v140, v153
	v_fma_f32 v125, v125, v140, v155
	v_lshlrev_b32_e32 v153, 16, v175
	v_bfe_i32 v154, v222, 8, 4
	v_and_b32_e32 v155, 0xffff0000, v175
	v_bfe_i32 v156, v222, 12, 4
	v_lshl_add_u32 v153, v154, 12, v153
	v_lshl_add_u32 v155, v156, 12, v155
	v_fma_f32 v126, v126, v140, v153
	v_fma_f32 v127, v127, v140, v155
	v_lshlrev_b32_e32 v153, 16, v176
	v_bfe_i32 v154, v222, 16, 4
	v_and_b32_e32 v155, 0xffff0000, v176
	v_bfe_i32 v156, v222, 20, 4
	v_lshl_add_u32 v153, v154, 12, v153
	v_lshl_add_u32 v155, v156, 12, v155
	v_fma_f32 v120, v120, v140, v153
	v_fma_f32 v121, v121, v140, v155
	v_lshlrev_b32_e32 v153, 16, v177
	v_bfe_i32 v154, v222, 24, 4
	v_and_b32_e32 v155, 0xffff0000, v177
	v_bfe_i32 v156, v222, 28, 4
	v_lshl_add_u32 v153, v154, 12, v153
	v_lshl_add_u32 v155, v156, 12, v155
	v_fma_f32 v122, v122, v140, v153
	v_fma_f32 v123, v123, v140, v155
	v_add_u32_e32 v153, 0x8800, v124
	v_add_u32_e32 v154, 0x8800, v125
	v_perm_b32 v174, v154, v153, s39
	v_bfe_u32 v155, v153, 12, 4
	v_lshrrev_b32_e32 v156, 8, v154
	v_and_or_b32 v222, v156, s40, v155
	v_mul_f32_e32 v238, v124, v124
	v_fmac_f32_e32 v238, v125, v125
	v_add_u32_e32 v153, 0x8800, v126
	v_add_u32_e32 v154, 0x8800, v127
	v_perm_b32 v175, v154, v153, s39
	v_bfe_u32 v155, v153, 12, 4
	v_lshrrev_b32_e32 v156, 8, v154
	v_and_or_b32 v157, v156, s40, v155
	v_lshl_or_b32 v222, v157, 8, v222
	v_fmac_f32_e32 v238, v126, v126
	v_fmac_f32_e32 v238, v127, v127
	v_add_u32_e32 v153, 0x8800, v120
	v_add_u32_e32 v154, 0x8800, v121
	v_perm_b32 v176, v154, v153, s39
	v_bfe_u32 v155, v153, 12, 4
	v_lshrrev_b32_e32 v156, 8, v154
	v_and_or_b32 v157, v156, s40, v155
	v_lshl_or_b32 v222, v157, 16, v222
	v_fmac_f32_e32 v238, v120, v120
	v_fmac_f32_e32 v238, v121, v121
	v_add_u32_e32 v153, 0x8800, v122
	v_add_u32_e32 v154, 0x8800, v123
	v_perm_b32 v177, v154, v153, s39
	v_bfe_u32 v155, v153, 12, 4
	v_lshrrev_b32_e32 v156, 8, v154
	v_and_or_b32 v157, v156, s40, v155
	v_lshl_or_b32 v222, v157, 24, v222
	v_fmac_f32_e32 v238, v122, v122
	v_fmac_f32_e32 v238, v123, v123
	v_xor_b32_e32 v222, 0x88888888, v222
	global_store_dwordx4 v151, v[174:177], s[34:35] offset:0
	s_waitcnt vmcnt(25)
	v_lshlrev_b32_e32 v153, 16, v178
	v_bfe_i32 v154, v223, 0, 4
	v_and_b32_e32 v155, 0xffff0000, v178
	v_bfe_i32 v156, v223, 4, 4
	v_lshl_add_u32 v153, v154, 12, v153
	v_lshl_add_u32 v155, v156, 12, v155
	v_fma_f32 v116, v116, v140, v153
	v_fma_f32 v117, v117, v140, v155
	v_lshlrev_b32_e32 v153, 16, v179
	v_bfe_i32 v154, v223, 8, 4
	v_and_b32_e32 v155, 0xffff0000, v179
	v_bfe_i32 v156, v223, 12, 4
	v_lshl_add_u32 v153, v154, 12, v153
	v_lshl_add_u32 v155, v156, 12, v155
	v_fma_f32 v118, v118, v140, v153
	v_fma_f32 v119, v119, v140, v155
	global_store_dword v[148:149], v222, off offset:0
	v_lshlrev_b32_e32 v153, 16, v180
	v_bfe_i32 v154, v223, 16, 4
	v_and_b32_e32 v155, 0xffff0000, v180
	v_bfe_i32 v156, v223, 20, 4
	v_lshl_add_u32 v153, v154, 12, v153
	v_lshl_add_u32 v155, v156, 12, v155
	v_fma_f32 v112, v112, v140, v153
	v_fma_f32 v113, v113, v140, v155
	v_lshlrev_b32_e32 v153, 16, v181
	v_bfe_i32 v154, v223, 24, 4
	v_and_b32_e32 v155, 0xffff0000, v181
	v_bfe_i32 v156, v223, 28, 4
	v_lshl_add_u32 v153, v154, 12, v153
	v_lshl_add_u32 v155, v156, 12, v155
	v_fma_f32 v114, v114, v140, v153
	v_fma_f32 v115, v115, v140, v155
	v_add_u32_e32 v153, 0x8800, v116
	v_add_u32_e32 v154, 0x8800, v117
	v_perm_b32 v178, v154, v153, s39
	v_bfe_u32 v155, v153, 12, 4
	v_lshrrev_b32_e32 v156, 8, v154
	v_and_or_b32 v223, v156, s40, v155
	v_fmac_f32_e32 v238, v116, v116
	v_fmac_f32_e32 v238, v117, v117
	v_add_u32_e32 v153, 0x8800, v118
	v_add_u32_e32 v154, 0x8800, v119
	v_perm_b32 v179, v154, v153, s39
	v_bfe_u32 v155, v153, 12, 4
	v_lshrrev_b32_e32 v156, 8, v154
	v_and_or_b32 v157, v156, s40, v155
	v_lshl_or_b32 v223, v157, 8, v223
	v_fmac_f32_e32 v238, v118, v118
	v_fmac_f32_e32 v238, v119, v119
	v_add_u32_e32 v153, 0x8800, v112
	v_add_u32_e32 v154, 0x8800, v113
	v_perm_b32 v180, v154, v153, s39
	v_bfe_u32 v155, v153, 12, 4
	v_lshrrev_b32_e32 v156, 8, v154
	v_and_or_b32 v157, v156, s40, v155
	v_lshl_or_b32 v223, v157, 16, v223
	v_fmac_f32_e32 v238, v112, v112
	v_fmac_f32_e32 v238, v113, v113
	v_add_u32_e32 v153, 0x8800, v114
	v_add_u32_e32 v154, 0x8800, v115
	v_perm_b32 v181, v154, v153, s39
	v_bfe_u32 v155, v153, 12, 4
	v_lshrrev_b32_e32 v156, 8, v154
	v_and_or_b32 v157, v156, s40, v155
	v_lshl_or_b32 v223, v157, 24, v223
	v_fmac_f32_e32 v238, v114, v114
	v_fmac_f32_e32 v238, v115, v115
	v_xor_b32_e32 v223, 0x88888888, v223
	global_store_dwordx4 v151, v[178:181], s[34:35] offset:256
	v_add_u32_e32 v151, 0x8000, v151
	s_waitcnt vmcnt(25)
	v_lshlrev_b32_e32 v153, 16, v182
	v_bfe_i32 v154, v224, 0, 4
	v_and_b32_e32 v155, 0xffff0000, v182
	v_bfe_i32 v156, v224, 4, 4
	v_lshl_add_u32 v153, v154, 12, v153
	v_lshl_add_u32 v155, v156, 12, v155
	v_fma_f32 v108, v108, v140, v153
	v_fma_f32 v109, v109, v140, v155
	v_lshlrev_b32_e32 v153, 16, v183
	v_bfe_i32 v154, v224, 8, 4
	v_and_b32_e32 v155, 0xffff0000, v183
	v_bfe_i32 v156, v224, 12, 4
	v_lshl_add_u32 v153, v154, 12, v153
	v_lshl_add_u32 v155, v156, 12, v155
	v_fma_f32 v110, v110, v140, v153
	v_fma_f32 v111, v111, v140, v155
	global_store_dword v[148:149], v223, off offset:256
	v_lshlrev_b32_e32 v153, 16, v184
	v_bfe_i32 v154, v224, 16, 4
	v_and_b32_e32 v155, 0xffff0000, v184
	v_bfe_i32 v156, v224, 20, 4
	v_lshl_add_u32 v153, v154, 12, v153
	v_lshl_add_u32 v155, v156, 12, v155
	v_fma_f32 v104, v104, v140, v153
	v_fma_f32 v105, v105, v140, v155
	v_lshlrev_b32_e32 v153, 16, v185
	v_bfe_i32 v154, v224, 24, 4
	v_and_b32_e32 v155, 0xffff0000, v185
	v_bfe_i32 v156, v224, 28, 4
	v_lshl_add_u32 v153, v154, 12, v153
	v_lshl_add_u32 v155, v156, 12, v155
	v_fma_f32 v106, v106, v140, v153
	v_fma_f32 v107, v107, v140, v155
	v_add_u32_e32 v153, 0x8800, v108
	v_add_u32_e32 v154, 0x8800, v109
	v_perm_b32 v182, v154, v153, s39
	v_bfe_u32 v155, v153, 12, 4
	v_lshrrev_b32_e32 v156, 8, v154
	v_and_or_b32 v224, v156, s40, v155
	v_mul_f32_e32 v239, v108, v108
	v_fmac_f32_e32 v239, v109, v109
	v_add_u32_e32 v153, 0x8800, v110
	v_add_u32_e32 v154, 0x8800, v111
	v_perm_b32 v183, v154, v153, s39
	v_bfe_u32 v155, v153, 12, 4
	v_lshrrev_b32_e32 v156, 8, v154
	v_and_or_b32 v157, v156, s40, v155
	v_lshl_or_b32 v224, v157, 8, v224
	v_fmac_f32_e32 v239, v110, v110
	v_fmac_f32_e32 v239, v111, v111
	v_add_u32_e32 v153, 0x8800, v104
	v_add_u32_e32 v154, 0x8800, v105
	v_perm_b32 v184, v154, v153, s39
	v_bfe_u32 v155, v153, 12, 4
	v_lshrrev_b32_e32 v156, 8, v154
	v_and_or_b32 v157, v156, s40, v155
	v_lshl_or_b32 v224, v157, 16, v224
	v_fmac_f32_e32 v239, v104, v104
	v_fmac_f32_e32 v239, v105, v105
	v_add_u32_e32 v153, 0x8800, v106
	v_add_u32_e32 v154, 0x8800, v107
	v_perm_b32 v185, v154, v153, s39
	v_bfe_u32 v155, v153, 12, 4
	v_lshrrev_b32_e32 v156, 8, v154
	v_and_or_b32 v157, v156, s40, v155
	v_lshl_or_b32 v224, v157, 24, v224
	v_fmac_f32_e32 v239, v106, v106
	v_fmac_f32_e32 v239, v107, v107
	v_xor_b32_e32 v224, 0x88888888, v224
	global_store_dwordx4 v151, v[182:185], s[34:35] offset:0
	s_waitcnt vmcnt(25)
	v_lshlrev_b32_e32 v153, 16, v186
	v_bfe_i32 v154, v225, 0, 4
	v_and_b32_e32 v155, 0xffff0000, v186
	v_bfe_i32 v156, v225, 4, 4
	v_lshl_add_u32 v153, v154, 12, v153
	v_lshl_add_u32 v155, v156, 12, v155
	v_fma_f32 v100, v100, v140, v153
	v_fma_f32 v101, v101, v140, v155
	v_lshlrev_b32_e32 v153, 16, v187
	v_bfe_i32 v154, v225, 8, 4
	v_and_b32_e32 v155, 0xffff0000, v187
	v_bfe_i32 v156, v225, 12, 4
	v_lshl_add_u32 v153, v154, 12, v153
	v_lshl_add_u32 v155, v156, 12, v155
	v_fma_f32 v102, v102, v140, v153
	v_fma_f32 v103, v103, v140, v155
	global_store_dword v[148:149], v224, off offset:512
	v_lshlrev_b32_e32 v153, 16, v188
	v_bfe_i32 v154, v225, 16, 4
	v_and_b32_e32 v155, 0xffff0000, v188
	v_bfe_i32 v156, v225, 20, 4
	v_lshl_add_u32 v153, v154, 12, v153
	v_lshl_add_u32 v155, v156, 12, v155
	v_fma_f32 v96, v96, v140, v153
	v_fma_f32 v97, v97, v140, v155
	v_lshlrev_b32_e32 v153, 16, v189
	v_bfe_i32 v154, v225, 24, 4
	v_and_b32_e32 v155, 0xffff0000, v189
	v_bfe_i32 v156, v225, 28, 4
	v_lshl_add_u32 v153, v154, 12, v153
	v_lshl_add_u32 v155, v156, 12, v155
	v_fma_f32 v98, v98, v140, v153
	v_fma_f32 v99, v99, v140, v155
	v_add_u32_e32 v153, 0x8800, v100
	v_add_u32_e32 v154, 0x8800, v101
	v_perm_b32 v186, v154, v153, s39
	v_bfe_u32 v155, v153, 12, 4
	v_lshrrev_b32_e32 v156, 8, v154
	v_and_or_b32 v225, v156, s40, v155
	v_fmac_f32_e32 v239, v100, v100
	v_fmac_f32_e32 v239, v101, v101
	v_add_u32_e32 v153, 0x8800, v102
	v_add_u32_e32 v154, 0x8800, v103
	v_perm_b32 v187, v154, v153, s39
	v_bfe_u32 v155, v153, 12, 4
	v_lshrrev_b32_e32 v156, 8, v154
	v_and_or_b32 v157, v156, s40, v155
	v_lshl_or_b32 v225, v157, 8, v225
	v_fmac_f32_e32 v239, v102, v102
	v_fmac_f32_e32 v239, v103, v103
	v_add_u32_e32 v153, 0x8800, v96
	v_add_u32_e32 v154, 0x8800, v97
	v_perm_b32 v188, v154, v153, s39
	v_bfe_u32 v155, v153, 12, 4
	v_lshrrev_b32_e32 v156, 8, v154
	v_and_or_b32 v157, v156, s40, v155
	v_lshl_or_b32 v225, v157, 16, v225
	v_fmac_f32_e32 v239, v96, v96
	v_fmac_f32_e32 v239, v97, v97
	v_add_u32_e32 v153, 0x8800, v98
	v_add_u32_e32 v154, 0x8800, v99
	v_perm_b32 v189, v154, v153, s39
	v_bfe_u32 v155, v153, 12, 4
	v_lshrrev_b32_e32 v156, 8, v154
	v_and_or_b32 v157, v156, s40, v155
	v_lshl_or_b32 v225, v157, 24, v225
	v_fmac_f32_e32 v239, v98, v98
	v_fmac_f32_e32 v239, v99, v99
	v_xor_b32_e32 v225, 0x88888888, v225
	global_store_dwordx4 v151, v[186:189], s[34:35] offset:256
	v_add_u32_e32 v151, 0x8000, v151
	global_store_dword v[148:149], v225, off offset:768
	s_nop 1
	global_load_dwordx4 v[174:177], v150, s[34:35] offset:0
	global_load_dwordx4 v[178:181], v150, s[34:35] offset:256
	v_add_u32_e32 v150, 0x8000, v150
	global_load_dwordx4 v[182:185], v150, s[34:35] offset:0
	global_load_dwordx4 v[186:189], v150, s[34:35] offset:256
	s_waitcnt vmcnt(30)
	v_lshlrev_b32_e32 v153, 16, v190
	v_bfe_i32 v154, v226, 0, 4
	v_and_b32_e32 v155, 0xffff0000, v190
	v_bfe_i32 v156, v226, 4, 4
	v_lshl_add_u32 v153, v154, 12, v153
	v_lshl_add_u32 v155, v156, 12, v155
	v_fma_f32 v92, v92, v140, v153
	v_fma_f32 v93, v93, v140, v155
	v_lshlrev_b32_e32 v153, 16, v191
	v_bfe_i32 v154, v226, 8, 4
	v_and_b32_e32 v155, 0xffff0000, v191
	v_bfe_i32 v156, v226, 12, 4
	v_lshl_add_u32 v153, v154, 12, v153
	v_lshl_add_u32 v155, v156, 12, v155
	v_fma_f32 v94, v94, v140, v153
	v_fma_f32 v95, v95, v140, v155
	v_lshlrev_b32_e32 v153, 16, v192
	v_bfe_i32 v154, v226, 16, 4
	v_and_b32_e32 v155, 0xffff0000, v192
	v_bfe_i32 v156, v226, 20, 4
	v_lshl_add_u32 v153, v154, 12, v153
	v_lshl_add_u32 v155, v156, 12, v155
	v_fma_f32 v88, v88, v140, v153
	v_fma_f32 v89, v89, v140, v155
	v_lshlrev_b32_e32 v153, 16, v193
	v_bfe_i32 v154, v226, 24, 4
	v_and_b32_e32 v155, 0xffff0000, v193
	v_bfe_i32 v156, v226, 28, 4
	v_lshl_add_u32 v153, v154, 12, v153
	v_lshl_add_u32 v155, v156, 12, v155
	v_fma_f32 v90, v90, v140, v153
	v_fma_f32 v91, v91, v140, v155
	v_add_u32_e32 v153, 0x8800, v92
	v_add_u32_e32 v154, 0x8800, v93
	v_perm_b32 v190, v154, v153, s39
	v_bfe_u32 v155, v153, 12, 4
	v_lshrrev_b32_e32 v156, 8, v154
	v_and_or_b32 v226, v156, s40, v155
	v_mul_f32_e32 v240, v92, v92
	v_fmac_f32_e32 v240, v93, v93
	v_add_u32_e32 v153, 0x8800, v94
	v_add_u32_e32 v154, 0x8800, v95
	v_perm_b32 v191, v154, v153, s39
	v_bfe_u32 v155, v153, 12, 4
	v_lshrrev_b32_e32 v156, 8, v154
	v_and_or_b32 v157, v156, s40, v155
	v_lshl_or_b32 v226, v157, 8, v226
	v_fmac_f32_e32 v240, v94, v94
	v_fmac_f32_e32 v240, v95, v95
	v_add_u32_e32 v153, 0x8800, v88
	v_add_u32_e32 v154, 0x8800, v89
	v_perm_b32 v192, v154, v153, s39
	v_bfe_u32 v155, v153, 12, 4
	v_lshrrev_b32_e32 v156, 8, v154
	v_and_or_b32 v157, v156, s40, v155
	v_lshl_or_b32 v226, v157, 16, v226
	v_fmac_f32_e32 v240, v88, v88
	v_fmac_f32_e32 v240, v89, v89
	v_add_u32_e32 v153, 0x8800, v90
	v_add_u32_e32 v154, 0x8800, v91
	v_perm_b32 v193, v154, v153, s39
	v_bfe_u32 v155, v153, 12, 4
	v_lshrrev_b32_e32 v156, 8, v154
	v_and_or_b32 v157, v156, s40, v155
	v_lshl_or_b32 v226, v157, 24, v226
	v_fmac_f32_e32 v240, v90, v90
	v_fmac_f32_e32 v240, v91, v91
	v_xor_b32_e32 v226, 0x88888888, v226
	global_store_dwordx4 v151, v[190:193], s[34:35] offset:0
	s_waitcnt vmcnt(29)
	v_lshlrev_b32_e32 v153, 16, v194
	v_bfe_i32 v154, v227, 0, 4
	v_and_b32_e32 v155, 0xffff0000, v194
	v_bfe_i32 v156, v227, 4, 4
	v_lshl_add_u32 v153, v154, 12, v153
	v_lshl_add_u32 v155, v156, 12, v155
	v_fma_f32 v84, v84, v140, v153
	v_fma_f32 v85, v85, v140, v155
	v_lshlrev_b32_e32 v153, 16, v195
	v_bfe_i32 v154, v227, 8, 4
	v_and_b32_e32 v155, 0xffff0000, v195
	v_bfe_i32 v156, v227, 12, 4
	v_lshl_add_u32 v153, v154, 12, v153
	v_lshl_add_u32 v155, v156, 12, v155
	v_fma_f32 v86, v86, v140, v153
	v_fma_f32 v87, v87, v140, v155
	global_store_dword v[148:149], v226, off offset:1024
	v_lshlrev_b32_e32 v153, 16, v196
	v_bfe_i32 v154, v227, 16, 4
	v_and_b32_e32 v155, 0xffff0000, v196
	v_bfe_i32 v156, v227, 20, 4
	v_lshl_add_u32 v153, v154, 12, v153
	v_lshl_add_u32 v155, v156, 12, v155
	v_fma_f32 v80, v80, v140, v153
	v_fma_f32 v81, v81, v140, v155
	v_lshlrev_b32_e32 v153, 16, v197
	v_bfe_i32 v154, v227, 24, 4
	v_and_b32_e32 v155, 0xffff0000, v197
	v_bfe_i32 v156, v227, 28, 4
	v_lshl_add_u32 v153, v154, 12, v153
	v_lshl_add_u32 v155, v156, 12, v155
	v_fma_f32 v82, v82, v140, v153
	v_fma_f32 v83, v83, v140, v155
	v_add_u32_e32 v153, 0x8800, v84
	v_add_u32_e32 v154, 0x8800, v85
	v_perm_b32 v194, v154, v153, s39
	v_bfe_u32 v155, v153, 12, 4
	v_lshrrev_b32_e32 v156, 8, v154
	v_and_or_b32 v227, v156, s40, v155
	v_fmac_f32_e32 v240, v84, v84
	v_fmac_f32_e32 v240, v85, v85
	v_add_u32_e32 v153, 0x8800, v86
	v_add_u32_e32 v154, 0x8800, v87
	v_perm_b32 v195, v154, v153, s39
	v_bfe_u32 v155, v153, 12, 4
	v_lshrrev_b32_e32 v156, 8, v154
	v_and_or_b32 v157, v156, s40, v155
	v_lshl_or_b32 v227, v157, 8, v227
	v_fmac_f32_e32 v240, v86, v86
	v_fmac_f32_e32 v240, v87, v87
	v_add_u32_e32 v153, 0x8800, v80
	v_add_u32_e32 v154, 0x8800, v81
	v_perm_b32 v196, v154, v153, s39
	v_bfe_u32 v155, v153, 12, 4
	v_lshrrev_b32_e32 v156, 8, v154
	v_and_or_b32 v157, v156, s40, v155
	v_lshl_or_b32 v227, v157, 16, v227
	v_fmac_f32_e32 v240, v80, v80
	v_fmac_f32_e32 v240, v81, v81
	v_add_u32_e32 v153, 0x8800, v82
	v_add_u32_e32 v154, 0x8800, v83
	v_perm_b32 v197, v154, v153, s39
	v_bfe_u32 v155, v153, 12, 4
	v_lshrrev_b32_e32 v156, 8, v154
	v_and_or_b32 v157, v156, s40, v155
	v_lshl_or_b32 v227, v157, 24, v227
	v_fmac_f32_e32 v240, v82, v82
	v_fmac_f32_e32 v240, v83, v83
	v_xor_b32_e32 v227, 0x88888888, v227
	global_store_dwordx4 v151, v[194:197], s[34:35] offset:256
	v_add_u32_e32 v151, 0x8000, v151
	s_waitcnt vmcnt(29)
	v_lshlrev_b32_e32 v153, 16, v198
	v_bfe_i32 v154, v228, 0, 4
	v_and_b32_e32 v155, 0xffff0000, v198
	v_bfe_i32 v156, v228, 4, 4
	v_lshl_add_u32 v153, v154, 12, v153
	v_lshl_add_u32 v155, v156, 12, v155
	v_fma_f32 v76, v76, v140, v153
	v_fma_f32 v77, v77, v140, v155
	v_lshlrev_b32_e32 v153, 16, v199
	v_bfe_i32 v154, v228, 8, 4
	v_and_b32_e32 v155, 0xffff0000, v199
	v_bfe_i32 v156, v228, 12, 4
	v_lshl_add_u32 v153, v154, 12, v153
	v_lshl_add_u32 v155, v156, 12, v155
	v_fma_f32 v78, v78, v140, v153
	v_fma_f32 v79, v79, v140, v155
	global_store_dword v[148:149], v227, off offset:1280
	v_lshlrev_b32_e32 v153, 16, v200
	v_bfe_i32 v154, v228, 16, 4
	v_and_b32_e32 v155, 0xffff0000, v200
	v_bfe_i32 v156, v228, 20, 4
	v_lshl_add_u32 v153, v154, 12, v153
	v_lshl_add_u32 v155, v156, 12, v155
	v_fma_f32 v72, v72, v140, v153
	v_fma_f32 v73, v73, v140, v155
	v_lshlrev_b32_e32 v153, 16, v201
	v_bfe_i32 v154, v228, 24, 4
	v_and_b32_e32 v155, 0xffff0000, v201
	v_bfe_i32 v156, v228, 28, 4
	v_lshl_add_u32 v153, v154, 12, v153
	v_lshl_add_u32 v155, v156, 12, v155
	v_fma_f32 v74, v74, v140, v153
	v_fma_f32 v75, v75, v140, v155
	v_add_u32_e32 v153, 0x8800, v76
	v_add_u32_e32 v154, 0x8800, v77
	v_perm_b32 v198, v154, v153, s39
	v_bfe_u32 v155, v153, 12, 4
	v_lshrrev_b32_e32 v156, 8, v154
	v_and_or_b32 v228, v156, s40, v155
	v_mul_f32_e32 v241, v76, v76
	v_fmac_f32_e32 v241, v77, v77
	v_add_u32_e32 v153, 0x8800, v78
	v_add_u32_e32 v154, 0x8800, v79
	v_perm_b32 v199, v154, v153, s39
	v_bfe_u32 v155, v153, 12, 4
	v_lshrrev_b32_e32 v156, 8, v154
	v_and_or_b32 v157, v156, s40, v155
	v_lshl_or_b32 v228, v157, 8, v228
	v_fmac_f32_e32 v241, v78, v78
	v_fmac_f32_e32 v241, v79, v79
	v_add_u32_e32 v153, 0x8800, v72
	v_add_u32_e32 v154, 0x8800, v73
	v_perm_b32 v200, v154, v153, s39
	v_bfe_u32 v155, v153, 12, 4
	v_lshrrev_b32_e32 v156, 8, v154
	v_and_or_b32 v157, v156, s40, v155
	v_lshl_or_b32 v228, v157, 16, v228
	v_fmac_f32_e32 v241, v72, v72
	v_fmac_f32_e32 v241, v73, v73
	v_add_u32_e32 v153, 0x8800, v74
	v_add_u32_e32 v154, 0x8800, v75
	v_perm_b32 v201, v154, v153, s39
	v_bfe_u32 v155, v153, 12, 4
	v_lshrrev_b32_e32 v156, 8, v154
	v_and_or_b32 v157, v156, s40, v155
	v_lshl_or_b32 v228, v157, 24, v228
	v_fmac_f32_e32 v241, v74, v74
	v_fmac_f32_e32 v241, v75, v75
	v_xor_b32_e32 v228, 0x88888888, v228
	global_store_dwordx4 v151, v[198:201], s[34:35] offset:0
	s_waitcnt vmcnt(29)
	v_lshlrev_b32_e32 v153, 16, v202
	v_bfe_i32 v154, v229, 0, 4
	v_and_b32_e32 v155, 0xffff0000, v202
	v_bfe_i32 v156, v229, 4, 4
	v_lshl_add_u32 v153, v154, 12, v153
	v_lshl_add_u32 v155, v156, 12, v155
	v_fma_f32 v68, v68, v140, v153
	v_fma_f32 v69, v69, v140, v155
	v_lshlrev_b32_e32 v153, 16, v203
	v_bfe_i32 v154, v229, 8, 4
	v_and_b32_e32 v155, 0xffff0000, v203
	v_bfe_i32 v156, v229, 12, 4
	v_lshl_add_u32 v153, v154, 12, v153
	v_lshl_add_u32 v155, v156, 12, v155
	v_fma_f32 v70, v70, v140, v153
	v_fma_f32 v71, v71, v140, v155
	global_store_dword v[148:149], v228, off offset:1536
	v_lshlrev_b32_e32 v153, 16, v204
	v_bfe_i32 v154, v229, 16, 4
	v_and_b32_e32 v155, 0xffff0000, v204
	v_bfe_i32 v156, v229, 20, 4
	v_lshl_add_u32 v153, v154, 12, v153
	v_lshl_add_u32 v155, v156, 12, v155
	v_fma_f32 v64, v64, v140, v153
	v_fma_f32 v65, v65, v140, v155
	v_lshlrev_b32_e32 v153, 16, v205
	v_bfe_i32 v154, v229, 24, 4
	v_and_b32_e32 v155, 0xffff0000, v205
	v_bfe_i32 v156, v229, 28, 4
	v_lshl_add_u32 v153, v154, 12, v153
	v_lshl_add_u32 v155, v156, 12, v155
	v_fma_f32 v66, v66, v140, v153
	v_fma_f32 v67, v67, v140, v155
	v_add_u32_e32 v153, 0x8800, v68
	v_add_u32_e32 v154, 0x8800, v69
	v_perm_b32 v202, v154, v153, s39
	v_bfe_u32 v155, v153, 12, 4
	v_lshrrev_b32_e32 v156, 8, v154
	v_and_or_b32 v229, v156, s40, v155
	v_fmac_f32_e32 v241, v68, v68
	v_fmac_f32_e32 v241, v69, v69
	v_add_u32_e32 v153, 0x8800, v70
	v_add_u32_e32 v154, 0x8800, v71
	v_perm_b32 v203, v154, v153, s39
	v_bfe_u32 v155, v153, 12, 4
	v_lshrrev_b32_e32 v156, 8, v154
	v_and_or_b32 v157, v156, s40, v155
	v_lshl_or_b32 v229, v157, 8, v229
	v_fmac_f32_e32 v241, v70, v70
	v_fmac_f32_e32 v241, v71, v71
	v_add_u32_e32 v153, 0x8800, v64
	v_add_u32_e32 v154, 0x8800, v65
	v_perm_b32 v204, v154, v153, s39
	v_bfe_u32 v155, v153, 12, 4
	v_lshrrev_b32_e32 v156, 8, v154
	v_and_or_b32 v157, v156, s40, v155
	v_lshl_or_b32 v229, v157, 16, v229
	v_fmac_f32_e32 v241, v64, v64
	v_fmac_f32_e32 v241, v65, v65
	v_add_u32_e32 v153, 0x8800, v66
	v_add_u32_e32 v154, 0x8800, v67
	v_perm_b32 v205, v154, v153, s39
	v_bfe_u32 v155, v153, 12, 4
	v_lshrrev_b32_e32 v156, 8, v154
	v_and_or_b32 v157, v156, s40, v155
	v_lshl_or_b32 v229, v157, 24, v229
	v_fmac_f32_e32 v241, v66, v66
	v_fmac_f32_e32 v241, v67, v67
	v_xor_b32_e32 v229, 0x88888888, v229
	global_store_dwordx4 v151, v[202:205], s[34:35] offset:256
	v_add_u32_e32 v151, 0x28000, v151
	global_store_dword v[148:149], v229, off offset:1792
	s_nop 1
	v_permlane32_swap_b32_e32 v238, v240
	v_permlane32_swap_b32_e32 v239, v241
	v_add_f32_e32 v153, v238, v240
	v_add_f32_e32 v154, v239, v241
	ds_swizzle_b32 v155, v153 offset:0x401f
	ds_swizzle_b32 v156, v154 offset:0x401f
	s_waitcnt lgkmcnt(0)
	v_add_f32_e32 v153, v153, v155
	v_add_f32_e32 v154, v154, v156
	v_cndmask_b32_e64 v153, v153, v154, s[24:25]
	global_store_dword v152, v153, s[88:89]
	s_waitcnt vmcnt(31)
	v_lshlrev_b32_e32 v153, 16, v206
	v_bfe_i32 v154, v230, 0, 4
	v_and_b32_e32 v155, 0xffff0000, v206
	v_bfe_i32 v156, v230, 4, 4
	v_lshl_add_u32 v153, v154, 12, v153
	v_lshl_add_u32 v155, v156, 12, v155
	v_fma_f32 v60, v60, v140, v153
	v_fma_f32 v61, v61, v140, v155
	v_lshlrev_b32_e32 v153, 16, v207
	v_bfe_i32 v154, v230, 8, 4
	v_and_b32_e32 v155, 0xffff0000, v207
	v_bfe_i32 v156, v230, 12, 4
	v_lshl_add_u32 v153, v154, 12, v153
	v_lshl_add_u32 v155, v156, 12, v155
	v_fma_f32 v62, v62, v140, v153
	v_fma_f32 v63, v63, v140, v155
	v_lshlrev_b32_e32 v153, 16, v208
	v_bfe_i32 v154, v230, 16, 4
	v_and_b32_e32 v155, 0xffff0000, v208
	v_bfe_i32 v156, v230, 20, 4
	v_lshl_add_u32 v153, v154, 12, v153
	v_lshl_add_u32 v155, v156, 12, v155
	v_fma_f32 v56, v56, v140, v153
	v_fma_f32 v57, v57, v140, v155
	v_lshlrev_b32_e32 v153, 16, v209
	v_bfe_i32 v154, v230, 24, 4
	v_and_b32_e32 v155, 0xffff0000, v209
	v_bfe_i32 v156, v230, 28, 4
	v_lshl_add_u32 v153, v154, 12, v153
	v_lshl_add_u32 v155, v156, 12, v155
	v_fma_f32 v58, v58, v140, v153
	v_fma_f32 v59, v59, v140, v155
	v_add_u32_e32 v153, 0x8800, v60
	v_add_u32_e32 v154, 0x8800, v61
	v_perm_b32 v206, v154, v153, s39
	v_bfe_u32 v155, v153, 12, 4
	v_lshrrev_b32_e32 v156, 8, v154
	v_and_or_b32 v230, v156, s40, v155
	v_mul_f32_e32 v238, v60, v60
	v_fmac_f32_e32 v238, v61, v61
	v_add_u32_e32 v153, 0x8800, v62
	v_add_u32_e32 v154, 0x8800, v63
	v_perm_b32 v207, v154, v153, s39
	v_bfe_u32 v155, v153, 12, 4
	v_lshrrev_b32_e32 v156, 8, v154
	v_and_or_b32 v157, v156, s40, v155
	v_lshl_or_b32 v230, v157, 8, v230
	v_fmac_f32_e32 v238, v62, v62
	v_fmac_f32_e32 v238, v63, v63
	v_add_u32_e32 v153, 0x8800, v56
	v_add_u32_e32 v154, 0x8800, v57
	v_perm_b32 v208, v154, v153, s39
	v_bfe_u32 v155, v153, 12, 4
	v_lshrrev_b32_e32 v156, 8, v154
	v_and_or_b32 v157, v156, s40, v155
	v_lshl_or_b32 v230, v157, 16, v230
	v_fmac_f32_e32 v238, v56, v56
	v_fmac_f32_e32 v238, v57, v57
	v_add_u32_e32 v153, 0x8800, v58
	v_add_u32_e32 v154, 0x8800, v59
	v_perm_b32 v209, v154, v153, s39
	v_bfe_u32 v155, v153, 12, 4
	v_lshrrev_b32_e32 v156, 8, v154
	v_and_or_b32 v157, v156, s40, v155
	v_lshl_or_b32 v230, v157, 24, v230
	v_fmac_f32_e32 v238, v58, v58
	v_fmac_f32_e32 v238, v59, v59
	v_xor_b32_e32 v230, 0x88888888, v230
	global_store_dwordx4 v151, v[206:209], s[34:35] offset:0
	s_waitcnt vmcnt(30)
	v_lshlrev_b32_e32 v153, 16, v210
	v_bfe_i32 v154, v231, 0, 4
	v_and_b32_e32 v155, 0xffff0000, v210
	v_bfe_i32 v156, v231, 4, 4
	v_lshl_add_u32 v153, v154, 12, v153
	v_lshl_add_u32 v155, v156, 12, v155
	v_fma_f32 v52, v52, v140, v153
	v_fma_f32 v53, v53, v140, v155
	v_lshlrev_b32_e32 v153, 16, v211
	v_bfe_i32 v154, v231, 8, 4
	v_and_b32_e32 v155, 0xffff0000, v211
	v_bfe_i32 v156, v231, 12, 4
	v_lshl_add_u32 v153, v154, 12, v153
	v_lshl_add_u32 v155, v156, 12, v155
	v_fma_f32 v54, v54, v140, v153
	v_fma_f32 v55, v55, v140, v155
	global_store_dword v[148:149], v230, off offset:2048
	v_lshlrev_b32_e32 v153, 16, v212
	v_bfe_i32 v154, v231, 16, 4
	v_and_b32_e32 v155, 0xffff0000, v212
	v_bfe_i32 v156, v231, 20, 4
	v_lshl_add_u32 v153, v154, 12, v153
	v_lshl_add_u32 v155, v156, 12, v155
	v_fma_f32 v48, v48, v140, v153
	v_fma_f32 v49, v49, v140, v155
	v_lshlrev_b32_e32 v153, 16, v213
	v_bfe_i32 v154, v231, 24, 4
	v_and_b32_e32 v155, 0xffff0000, v213
	v_bfe_i32 v156, v231, 28, 4
	v_lshl_add_u32 v153, v154, 12, v153
	v_lshl_add_u32 v155, v156, 12, v155
	v_fma_f32 v50, v50, v140, v153
	v_fma_f32 v51, v51, v140, v155
	v_add_u32_e32 v153, 0x8800, v52
	v_add_u32_e32 v154, 0x8800, v53
	v_perm_b32 v210, v154, v153, s39
	v_bfe_u32 v155, v153, 12, 4
	v_lshrrev_b32_e32 v156, 8, v154
	v_and_or_b32 v231, v156, s40, v155
	v_fmac_f32_e32 v238, v52, v52
	v_fmac_f32_e32 v238, v53, v53
	v_add_u32_e32 v153, 0x8800, v54
	v_add_u32_e32 v154, 0x8800, v55
	v_perm_b32 v211, v154, v153, s39
	v_bfe_u32 v155, v153, 12, 4
	v_lshrrev_b32_e32 v156, 8, v154
	v_and_or_b32 v157, v156, s40, v155
	v_lshl_or_b32 v231, v157, 8, v231
	v_fmac_f32_e32 v238, v54, v54
	v_fmac_f32_e32 v238, v55, v55
	v_add_u32_e32 v153, 0x8800, v48
	v_add_u32_e32 v154, 0x8800, v49
	v_perm_b32 v212, v154, v153, s39
	v_bfe_u32 v155, v153, 12, 4
	v_lshrrev_b32_e32 v156, 8, v154
	v_and_or_b32 v157, v156, s40, v155
	v_lshl_or_b32 v231, v157, 16, v231
	v_fmac_f32_e32 v238, v48, v48
	v_fmac_f32_e32 v238, v49, v49
	v_add_u32_e32 v153, 0x8800, v50
	v_add_u32_e32 v154, 0x8800, v51
	v_perm_b32 v213, v154, v153, s39
	v_bfe_u32 v155, v153, 12, 4
	v_lshrrev_b32_e32 v156, 8, v154
	v_and_or_b32 v157, v156, s40, v155
	v_lshl_or_b32 v231, v157, 24, v231
	v_fmac_f32_e32 v238, v50, v50
	v_fmac_f32_e32 v238, v51, v51
	v_xor_b32_e32 v231, 0x88888888, v231
	global_store_dwordx4 v151, v[210:213], s[34:35] offset:256
	v_add_u32_e32 v151, 0x8000, v151
	s_waitcnt vmcnt(30)
	v_lshlrev_b32_e32 v153, 16, v214
	v_bfe_i32 v154, v232, 0, 4
	v_and_b32_e32 v155, 0xffff0000, v214
	v_bfe_i32 v156, v232, 4, 4
	v_lshl_add_u32 v153, v154, 12, v153
	v_lshl_add_u32 v155, v156, 12, v155
	v_fma_f32 v44, v44, v140, v153
	v_fma_f32 v45, v45, v140, v155
	v_lshlrev_b32_e32 v153, 16, v215
	v_bfe_i32 v154, v232, 8, 4
	v_and_b32_e32 v155, 0xffff0000, v215
	v_bfe_i32 v156, v232, 12, 4
	v_lshl_add_u32 v153, v154, 12, v153
	v_lshl_add_u32 v155, v156, 12, v155
	v_fma_f32 v46, v46, v140, v153
	v_fma_f32 v47, v47, v140, v155
	global_store_dword v[148:149], v231, off offset:2304
	v_lshlrev_b32_e32 v153, 16, v216
	v_bfe_i32 v154, v232, 16, 4
	v_and_b32_e32 v155, 0xffff0000, v216
	v_bfe_i32 v156, v232, 20, 4
	v_lshl_add_u32 v153, v154, 12, v153
	v_lshl_add_u32 v155, v156, 12, v155
	v_fma_f32 v40, v40, v140, v153
	v_fma_f32 v41, v41, v140, v155
	v_lshlrev_b32_e32 v153, 16, v217
	v_bfe_i32 v154, v232, 24, 4
	v_and_b32_e32 v155, 0xffff0000, v217
	v_bfe_i32 v156, v232, 28, 4
	v_lshl_add_u32 v153, v154, 12, v153
	v_lshl_add_u32 v155, v156, 12, v155
	v_fma_f32 v42, v42, v140, v153
	v_fma_f32 v43, v43, v140, v155
	v_add_u32_e32 v153, 0x8800, v44
	v_add_u32_e32 v154, 0x8800, v45
	v_perm_b32 v214, v154, v153, s39
	v_bfe_u32 v155, v153, 12, 4
	v_lshrrev_b32_e32 v156, 8, v154
	v_and_or_b32 v232, v156, s40, v155
	v_mul_f32_e32 v239, v44, v44
	v_fmac_f32_e32 v239, v45, v45
	v_add_u32_e32 v153, 0x8800, v46
	v_add_u32_e32 v154, 0x8800, v47
	v_perm_b32 v215, v154, v153, s39
	v_bfe_u32 v155, v153, 12, 4
	v_lshrrev_b32_e32 v156, 8, v154
	v_and_or_b32 v157, v156, s40, v155
	v_lshl_or_b32 v232, v157, 8, v232
	v_fmac_f32_e32 v239, v46, v46
	v_fmac_f32_e32 v239, v47, v47
	v_add_u32_e32 v153, 0x8800, v40
	v_add_u32_e32 v154, 0x8800, v41
	v_perm_b32 v216, v154, v153, s39
	v_bfe_u32 v155, v153, 12, 4
	v_lshrrev_b32_e32 v156, 8, v154
	v_and_or_b32 v157, v156, s40, v155
	v_lshl_or_b32 v232, v157, 16, v232
	v_fmac_f32_e32 v239, v40, v40
	v_fmac_f32_e32 v239, v41, v41
	v_add_u32_e32 v153, 0x8800, v42
	v_add_u32_e32 v154, 0x8800, v43
	v_perm_b32 v217, v154, v153, s39
	v_bfe_u32 v155, v153, 12, 4
	v_lshrrev_b32_e32 v156, 8, v154
	v_and_or_b32 v157, v156, s40, v155
	v_lshl_or_b32 v232, v157, 24, v232
	v_fmac_f32_e32 v239, v42, v42
	v_fmac_f32_e32 v239, v43, v43
	v_xor_b32_e32 v232, 0x88888888, v232
	global_store_dwordx4 v151, v[214:217], s[34:35] offset:0
	s_waitcnt vmcnt(30)
	v_lshlrev_b32_e32 v153, 16, v218
	v_bfe_i32 v154, v233, 0, 4
	v_and_b32_e32 v155, 0xffff0000, v218
	v_bfe_i32 v156, v233, 4, 4
	v_lshl_add_u32 v153, v154, 12, v153
	v_lshl_add_u32 v155, v156, 12, v155
	v_fma_f32 v36, v36, v140, v153
	v_fma_f32 v37, v37, v140, v155
	v_lshlrev_b32_e32 v153, 16, v219
	v_bfe_i32 v154, v233, 8, 4
	v_and_b32_e32 v155, 0xffff0000, v219
	v_bfe_i32 v156, v233, 12, 4
	v_lshl_add_u32 v153, v154, 12, v153
	v_lshl_add_u32 v155, v156, 12, v155
	v_fma_f32 v38, v38, v140, v153
	v_fma_f32 v39, v39, v140, v155
	global_store_dword v[148:149], v232, off offset:2560
	v_lshlrev_b32_e32 v153, 16, v220
	v_bfe_i32 v154, v233, 16, 4
	v_and_b32_e32 v155, 0xffff0000, v220
	v_bfe_i32 v156, v233, 20, 4
	v_lshl_add_u32 v153, v154, 12, v153
	v_lshl_add_u32 v155, v156, 12, v155
	v_fma_f32 v32, v32, v140, v153
	v_fma_f32 v33, v33, v140, v155
	v_lshlrev_b32_e32 v153, 16, v221
	v_bfe_i32 v154, v233, 24, 4
	v_and_b32_e32 v155, 0xffff0000, v221
	v_bfe_i32 v156, v233, 28, 4
	v_lshl_add_u32 v153, v154, 12, v153
	v_lshl_add_u32 v155, v156, 12, v155
	v_fma_f32 v34, v34, v140, v153
	v_fma_f32 v35, v35, v140, v155
	v_add_u32_e32 v153, 0x8800, v36
	v_add_u32_e32 v154, 0x8800, v37
	v_perm_b32 v218, v154, v153, s39
	v_bfe_u32 v155, v153, 12, 4
	v_lshrrev_b32_e32 v156, 8, v154
	v_and_or_b32 v233, v156, s40, v155
	v_fmac_f32_e32 v239, v36, v36
	v_fmac_f32_e32 v239, v37, v37
	v_add_u32_e32 v153, 0x8800, v38
	v_add_u32_e32 v154, 0x8800, v39
	v_perm_b32 v219, v154, v153, s39
	v_bfe_u32 v155, v153, 12, 4
	v_lshrrev_b32_e32 v156, 8, v154
	v_and_or_b32 v157, v156, s40, v155
	v_lshl_or_b32 v233, v157, 8, v233
	v_fmac_f32_e32 v239, v38, v38
	v_fmac_f32_e32 v239, v39, v39
	v_add_u32_e32 v153, 0x8800, v32
	v_add_u32_e32 v154, 0x8800, v33
	v_perm_b32 v220, v154, v153, s39
	v_bfe_u32 v155, v153, 12, 4
	v_lshrrev_b32_e32 v156, 8, v154
	v_and_or_b32 v157, v156, s40, v155
	v_lshl_or_b32 v233, v157, 16, v233
	v_fmac_f32_e32 v239, v32, v32
	v_fmac_f32_e32 v239, v33, v33
	v_add_u32_e32 v153, 0x8800, v34
	v_add_u32_e32 v154, 0x8800, v35
	v_perm_b32 v221, v154, v153, s39
	v_bfe_u32 v155, v153, 12, 4
	v_lshrrev_b32_e32 v156, 8, v154
	v_and_or_b32 v157, v156, s40, v155
	v_lshl_or_b32 v233, v157, 24, v233
	v_fmac_f32_e32 v239, v34, v34
	v_fmac_f32_e32 v239, v35, v35
	v_xor_b32_e32 v233, 0x88888888, v233
	global_store_dwordx4 v151, v[218:221], s[34:35] offset:256
	v_add_u32_e32 v151, 0x8000, v151
	s_waitcnt vmcnt(19)
	v_lshlrev_b32_e32 v153, 16, v174
	v_bfe_i32 v154, v234, 0, 4
	v_and_b32_e32 v155, 0xffff0000, v174
	v_bfe_i32 v156, v234, 4, 4
	v_lshl_add_u32 v153, v154, 12, v153
	v_lshl_add_u32 v155, v156, 12, v155
	v_fma_f32 v28, v28, v140, v153
	v_fma_f32 v29, v29, v140, v155
	v_lshlrev_b32_e32 v153, 16, v175
	v_bfe_i32 v154, v234, 8, 4
	v_and_b32_e32 v155, 0xffff0000, v175
	v_bfe_i32 v156, v234, 12, 4
	v_lshl_add_u32 v153, v154, 12, v153
	v_lshl_add_u32 v155, v156, 12, v155
	v_fma_f32 v30, v30, v140, v153
	v_fma_f32 v31, v31, v140, v155
	global_store_dword v[148:149], v233, off offset:2816
	v_lshlrev_b32_e32 v153, 16, v176
	v_bfe_i32 v154, v234, 16, 4
	v_and_b32_e32 v155, 0xffff0000, v176
	v_bfe_i32 v156, v234, 20, 4
	v_lshl_add_u32 v153, v154, 12, v153
	v_lshl_add_u32 v155, v156, 12, v155
	v_fma_f32 v24, v24, v140, v153
	v_fma_f32 v25, v25, v140, v155
	v_lshlrev_b32_e32 v153, 16, v177
	v_bfe_i32 v154, v234, 24, 4
	v_and_b32_e32 v155, 0xffff0000, v177
	v_bfe_i32 v156, v234, 28, 4
	v_lshl_add_u32 v153, v154, 12, v153
	v_lshl_add_u32 v155, v156, 12, v155
	v_fma_f32 v26, v26, v140, v153
	v_fma_f32 v27, v27, v140, v155
	v_add_u32_e32 v153, 0x8800, v28
	v_add_u32_e32 v154, 0x8800, v29
	v_perm_b32 v174, v154, v153, s39
	v_bfe_u32 v155, v153, 12, 4
	v_lshrrev_b32_e32 v156, 8, v154
	v_and_or_b32 v234, v156, s40, v155
	v_mul_f32_e32 v240, v28, v28
	v_fmac_f32_e32 v240, v29, v29
	v_add_u32_e32 v153, 0x8800, v30
	v_add_u32_e32 v154, 0x8800, v31
	v_perm_b32 v175, v154, v153, s39
	v_bfe_u32 v155, v153, 12, 4
	v_lshrrev_b32_e32 v156, 8, v154
	v_and_or_b32 v157, v156, s40, v155
	v_lshl_or_b32 v234, v157, 8, v234
	v_fmac_f32_e32 v240, v30, v30
	v_fmac_f32_e32 v240, v31, v31
	v_add_u32_e32 v153, 0x8800, v24
	v_add_u32_e32 v154, 0x8800, v25
	v_perm_b32 v176, v154, v153, s39
	v_bfe_u32 v155, v153, 12, 4
	v_lshrrev_b32_e32 v156, 8, v154
	v_and_or_b32 v157, v156, s40, v155
	v_lshl_or_b32 v234, v157, 16, v234
	v_fmac_f32_e32 v240, v24, v24
	v_fmac_f32_e32 v240, v25, v25
	v_add_u32_e32 v153, 0x8800, v26
	v_add_u32_e32 v154, 0x8800, v27
	v_perm_b32 v177, v154, v153, s39
	v_bfe_u32 v155, v153, 12, 4
	v_lshrrev_b32_e32 v156, 8, v154
	v_and_or_b32 v157, v156, s40, v155
	v_lshl_or_b32 v234, v157, 24, v234
	v_fmac_f32_e32 v240, v26, v26
	v_fmac_f32_e32 v240, v27, v27
	v_xor_b32_e32 v234, 0x88888888, v234
	global_store_dwordx4 v151, v[174:177], s[34:35] offset:0
	s_waitcnt vmcnt(20)
	v_lshlrev_b32_e32 v153, 16, v178
	v_bfe_i32 v154, v235, 0, 4
	v_and_b32_e32 v155, 0xffff0000, v178
	v_bfe_i32 v156, v235, 4, 4
	v_lshl_add_u32 v153, v154, 12, v153
	v_lshl_add_u32 v155, v156, 12, v155
	v_fma_f32 v20, v20, v140, v153
	v_fma_f32 v21, v21, v140, v155
	v_lshlrev_b32_e32 v153, 16, v179
	v_bfe_i32 v154, v235, 8, 4
	v_and_b32_e32 v155, 0xffff0000, v179
	v_bfe_i32 v156, v235, 12, 4
	v_lshl_add_u32 v153, v154, 12, v153
	v_lshl_add_u32 v155, v156, 12, v155
	v_fma_f32 v22, v22, v140, v153
	v_fma_f32 v23, v23, v140, v155
	global_store_dword v[148:149], v234, off offset:3072
	v_lshlrev_b32_e32 v153, 16, v180
	v_bfe_i32 v154, v235, 16, 4
	v_and_b32_e32 v155, 0xffff0000, v180
	v_bfe_i32 v156, v235, 20, 4
	v_lshl_add_u32 v153, v154, 12, v153
	v_lshl_add_u32 v155, v156, 12, v155
	v_fma_f32 v16, v16, v140, v153
	v_fma_f32 v17, v17, v140, v155
	v_lshlrev_b32_e32 v153, 16, v181
	v_bfe_i32 v154, v235, 24, 4
	v_and_b32_e32 v155, 0xffff0000, v181
	v_bfe_i32 v156, v235, 28, 4
	v_lshl_add_u32 v153, v154, 12, v153
	v_lshl_add_u32 v155, v156, 12, v155
	v_fma_f32 v18, v18, v140, v153
	v_fma_f32 v19, v19, v140, v155
	v_add_u32_e32 v153, 0x8800, v20
	v_add_u32_e32 v154, 0x8800, v21
	v_perm_b32 v178, v154, v153, s39
	v_bfe_u32 v155, v153, 12, 4
	v_lshrrev_b32_e32 v156, 8, v154
	v_and_or_b32 v235, v156, s40, v155
	v_fmac_f32_e32 v240, v20, v20
	v_fmac_f32_e32 v240, v21, v21
	v_add_u32_e32 v153, 0x8800, v22
	v_add_u32_e32 v154, 0x8800, v23
	v_perm_b32 v179, v154, v153, s39
	v_bfe_u32 v155, v153, 12, 4
	v_lshrrev_b32_e32 v156, 8, v154
	v_and_or_b32 v157, v156, s40, v155
	v_lshl_or_b32 v235, v157, 8, v235
	v_fmac_f32_e32 v240, v22, v22
	v_fmac_f32_e32 v240, v23, v23
	v_add_u32_e32 v153, 0x8800, v16
	v_add_u32_e32 v154, 0x8800, v17
	v_perm_b32 v180, v154, v153, s39
	v_bfe_u32 v155, v153, 12, 4
	v_lshrrev_b32_e32 v156, 8, v154
	v_and_or_b32 v157, v156, s40, v155
	v_lshl_or_b32 v235, v157, 16, v235
	v_fmac_f32_e32 v240, v16, v16
	v_fmac_f32_e32 v240, v17, v17
	v_add_u32_e32 v153, 0x8800, v18
	v_add_u32_e32 v154, 0x8800, v19
	v_perm_b32 v181, v154, v153, s39
	v_bfe_u32 v155, v153, 12, 4
	v_lshrrev_b32_e32 v156, 8, v154
	v_and_or_b32 v157, v156, s40, v155
	v_lshl_or_b32 v235, v157, 24, v235
	v_fmac_f32_e32 v240, v18, v18
	v_fmac_f32_e32 v240, v19, v19
	v_xor_b32_e32 v235, 0x88888888, v235
	global_store_dwordx4 v151, v[178:181], s[34:35] offset:256
	v_add_u32_e32 v151, 0x8000, v151
	s_waitcnt vmcnt(21)
	v_lshlrev_b32_e32 v153, 16, v182
	v_bfe_i32 v154, v236, 0, 4
	v_and_b32_e32 v155, 0xffff0000, v182
	v_bfe_i32 v156, v236, 4, 4
	v_lshl_add_u32 v153, v154, 12, v153
	v_lshl_add_u32 v155, v156, 12, v155
	v_fma_f32 v12, v12, v140, v153
	v_fma_f32 v13, v13, v140, v155
	v_lshlrev_b32_e32 v153, 16, v183
	v_bfe_i32 v154, v236, 8, 4
	v_and_b32_e32 v155, 0xffff0000, v183
	v_bfe_i32 v156, v236, 12, 4
	v_lshl_add_u32 v153, v154, 12, v153
	v_lshl_add_u32 v155, v156, 12, v155
	v_fma_f32 v14, v14, v140, v153
	v_fma_f32 v15, v15, v140, v155
	global_store_dword v[148:149], v235, off offset:3328
	v_lshlrev_b32_e32 v153, 16, v184
	v_bfe_i32 v154, v236, 16, 4
	v_and_b32_e32 v155, 0xffff0000, v184
	v_bfe_i32 v156, v236, 20, 4
	v_lshl_add_u32 v153, v154, 12, v153
	v_lshl_add_u32 v155, v156, 12, v155
	v_fma_f32 v8, v8, v140, v153
	v_fma_f32 v9, v9, v140, v155
	v_lshlrev_b32_e32 v153, 16, v185
	v_bfe_i32 v154, v236, 24, 4
	v_and_b32_e32 v155, 0xffff0000, v185
	v_bfe_i32 v156, v236, 28, 4
	v_lshl_add_u32 v153, v154, 12, v153
	v_lshl_add_u32 v155, v156, 12, v155
	v_fma_f32 v10, v10, v140, v153
	v_fma_f32 v11, v11, v140, v155
	v_add_u32_e32 v153, 0x8800, v12
	v_add_u32_e32 v154, 0x8800, v13
	v_perm_b32 v182, v154, v153, s39
	v_bfe_u32 v155, v153, 12, 4
	v_lshrrev_b32_e32 v156, 8, v154
	v_and_or_b32 v236, v156, s40, v155
	v_mul_f32_e32 v241, v12, v12
	v_fmac_f32_e32 v241, v13, v13
	v_add_u32_e32 v153, 0x8800, v14
	v_add_u32_e32 v154, 0x8800, v15
	v_perm_b32 v183, v154, v153, s39
	v_bfe_u32 v155, v153, 12, 4
	v_lshrrev_b32_e32 v156, 8, v154
	v_and_or_b32 v157, v156, s40, v155
	v_lshl_or_b32 v236, v157, 8, v236
	v_fmac_f32_e32 v241, v14, v14
	v_fmac_f32_e32 v241, v15, v15
	v_add_u32_e32 v153, 0x8800, v8
	v_add_u32_e32 v154, 0x8800, v9
	v_perm_b32 v184, v154, v153, s39
	v_bfe_u32 v155, v153, 12, 4
	v_lshrrev_b32_e32 v156, 8, v154
	v_and_or_b32 v157, v156, s40, v155
	v_lshl_or_b32 v236, v157, 16, v236
	v_fmac_f32_e32 v241, v8, v8
	v_fmac_f32_e32 v241, v9, v9
	v_add_u32_e32 v153, 0x8800, v10
	v_add_u32_e32 v154, 0x8800, v11
	v_perm_b32 v185, v154, v153, s39
	v_bfe_u32 v155, v153, 12, 4
	v_lshrrev_b32_e32 v156, 8, v154
	v_and_or_b32 v157, v156, s40, v155
	v_lshl_or_b32 v236, v157, 24, v236
	v_fmac_f32_e32 v241, v10, v10
	v_fmac_f32_e32 v241, v11, v11
	v_xor_b32_e32 v236, 0x88888888, v236
	global_store_dwordx4 v151, v[182:185], s[34:35] offset:0
	s_waitcnt vmcnt(22)
	v_lshlrev_b32_e32 v153, 16, v186
	v_bfe_i32 v154, v237, 0, 4
	v_and_b32_e32 v155, 0xffff0000, v186
	v_bfe_i32 v156, v237, 4, 4
	v_lshl_add_u32 v153, v154, 12, v153
	v_lshl_add_u32 v155, v156, 12, v155
	v_fma_f32 v0, v0, v140, v153
	v_fma_f32 v1, v1, v140, v155
	v_lshlrev_b32_e32 v153, 16, v187
	v_bfe_i32 v154, v237, 8, 4
	v_and_b32_e32 v155, 0xffff0000, v187
	v_bfe_i32 v156, v237, 12, 4
	v_lshl_add_u32 v153, v154, 12, v153
	v_lshl_add_u32 v155, v156, 12, v155
	v_fma_f32 v2, v2, v140, v153
	v_fma_f32 v3, v3, v140, v155
	global_store_dword v[148:149], v236, off offset:3584
	v_lshlrev_b32_e32 v153, 16, v188
	v_bfe_i32 v154, v237, 16, 4
	v_and_b32_e32 v155, 0xffff0000, v188
	v_bfe_i32 v156, v237, 20, 4
	v_lshl_add_u32 v153, v154, 12, v153
	v_lshl_add_u32 v155, v156, 12, v155
	v_fma_f32 v4, v4, v140, v153
	v_fma_f32 v5, v5, v140, v155
	v_lshlrev_b32_e32 v153, 16, v189
	v_bfe_i32 v154, v237, 24, 4
	v_and_b32_e32 v155, 0xffff0000, v189
	v_bfe_i32 v156, v237, 28, 4
	v_lshl_add_u32 v153, v154, 12, v153
	v_lshl_add_u32 v155, v156, 12, v155
	v_fma_f32 v6, v6, v140, v153
	v_fma_f32 v7, v7, v140, v155
	v_add_u32_e32 v153, 0x8800, v0
	v_add_u32_e32 v154, 0x8800, v1
	v_perm_b32 v186, v154, v153, s39
	v_bfe_u32 v155, v153, 12, 4
	v_lshrrev_b32_e32 v156, 8, v154
	v_and_or_b32 v237, v156, s40, v155
	v_fmac_f32_e32 v241, v0, v0
	v_fmac_f32_e32 v241, v1, v1
	v_add_u32_e32 v153, 0x8800, v2
	v_add_u32_e32 v154, 0x8800, v3
	v_perm_b32 v187, v154, v153, s39
	v_bfe_u32 v155, v153, 12, 4
	v_lshrrev_b32_e32 v156, 8, v154
	v_and_or_b32 v157, v156, s40, v155
	v_lshl_or_b32 v237, v157, 8, v237
	v_fmac_f32_e32 v241, v2, v2
	v_fmac_f32_e32 v241, v3, v3
	v_add_u32_e32 v153, 0x8800, v4
	v_add_u32_e32 v154, 0x8800, v5
	v_perm_b32 v188, v154, v153, s39
	v_bfe_u32 v155, v153, 12, 4
	v_lshrrev_b32_e32 v156, 8, v154
	v_and_or_b32 v157, v156, s40, v155
	v_lshl_or_b32 v237, v157, 16, v237
	v_fmac_f32_e32 v241, v4, v4
	v_fmac_f32_e32 v241, v5, v5
	v_add_u32_e32 v153, 0x8800, v6
	v_add_u32_e32 v154, 0x8800, v7
	v_perm_b32 v189, v154, v153, s39
	v_bfe_u32 v155, v153, 12, 4
	v_lshrrev_b32_e32 v156, 8, v154
	v_and_or_b32 v157, v156, s40, v155
	v_lshl_or_b32 v237, v157, 24, v237
	v_fmac_f32_e32 v241, v6, v6
	v_fmac_f32_e32 v241, v7, v7
	v_xor_b32_e32 v237, 0x88888888, v237
	global_store_dwordx4 v151, v[186:189], s[34:35] offset:256
	global_store_dword v[148:149], v237, off offset:3840
	s_nop 1
	v_permlane32_swap_b32_e32 v238, v240
	v_permlane32_swap_b32_e32 v239, v241
	v_add_f32_e32 v153, v238, v240
	v_add_f32_e32 v154, v239, v241
	ds_swizzle_b32 v155, v153 offset:0x401f
	ds_swizzle_b32 v156, v154 offset:0x401f
	s_waitcnt lgkmcnt(0)
	v_add_f32_e32 v153, v153, v155
	v_add_f32_e32 v154, v154, v156
	v_cndmask_b32_e64 v153, v153, v154, s[24:25]
	v_add_u32_e32 v152, 0x2000, v152
	global_store_dword v152, v153, s[88:89]
	s_branch .LBB0_340
.Lres_out:
	v_lshlrev_b32_e32 v156, 12, v153
	v_lshl_add_u32 v151, v154, 2, v156
	global_load_dwordx4 v[174:177], v150, s[34:35] offset:0
	global_load_dword v222, v[148:149], off offset:0
	global_load_dwordx4 v[178:181], v150, s[34:35] offset:256
	v_add_u32_e32 v150, 0x8000, v150
	global_load_dword v223, v[148:149], off offset:256
	global_load_dwordx4 v[182:185], v150, s[34:35] offset:0
	global_load_dword v224, v[148:149], off offset:512
	global_load_dwordx4 v[186:189], v150, s[34:35] offset:256
	v_add_u32_e32 v150, 0x8000, v150
	global_load_dword v225, v[148:149], off offset:768
	global_load_dwordx4 v[190:193], v150, s[34:35] offset:0
	global_load_dword v226, v[148:149], off offset:1024
	global_load_dwordx4 v[194:197], v150, s[34:35] offset:256
	v_add_u32_e32 v150, 0x8000, v150
	global_load_dword v227, v[148:149], off offset:1280
	global_load_dwordx4 v[198:201], v150, s[34:35] offset:0
	global_load_dword v228, v[148:149], off offset:1536
	global_load_dwordx4 v[202:205], v150, s[34:35] offset:256
	v_add_u32_e32 v150, 0x28000, v150
	global_load_dword v229, v[148:149], off offset:1792
	global_load_dwordx4 v[206:209], v150, s[34:35] offset:0
	global_load_dword v230, v[148:149], off offset:2048
	global_load_dwordx4 v[210:213], v150, s[34:35] offset:256
	v_add_u32_e32 v150, 0x8000, v150
	global_load_dword v231, v[148:149], off offset:2304
	global_load_dwordx4 v[214:217], v150, s[34:35] offset:0
	global_load_dword v232, v[148:149], off offset:2560
	global_load_dwordx4 v[218:221], v150, s[34:35] offset:256
	v_add_u32_e32 v150, 0x8000, v150
	global_load_dword v233, v[148:149], off offset:2816
	global_load_dword v234, v[148:149], off offset:3072
	global_load_dword v235, v[148:149], off offset:3328
	global_load_dword v236, v[148:149], off offset:3584
	global_load_dword v237, v[148:149], off offset:3840
	s_waitcnt vmcnt(26)
	v_lshlrev_b32_e32 v153, 16, v174
	v_bfe_i32 v154, v222, 0, 4
	v_and_b32_e32 v155, 0xffff0000, v174
	v_bfe_i32 v156, v222, 4, 4
	v_lshl_add_u32 v153, v154, 12, v153
	v_lshl_add_u32 v155, v156, 12, v155
	v_fma_f32 v124, v124, v140, v153
	v_fma_f32 v125, v125, v140, v155
	v_lshlrev_b32_e32 v153, 16, v175
	v_bfe_i32 v154, v222, 8, 4
	v_and_b32_e32 v155, 0xffff0000, v175
	v_bfe_i32 v156, v222, 12, 4
	v_lshl_add_u32 v153, v154, 12, v153
	v_lshl_add_u32 v155, v156, 12, v155
	v_fma_f32 v126, v126, v140, v153
	v_fma_f32 v127, v127, v140, v155
	v_lshlrev_b32_e32 v153, 16, v176
	v_bfe_i32 v154, v222, 16, 4
	v_and_b32_e32 v155, 0xffff0000, v176
	v_bfe_i32 v156, v222, 20, 4
	v_lshl_add_u32 v153, v154, 12, v153
	v_lshl_add_u32 v155, v156, 12, v155
	v_fma_f32 v120, v120, v140, v153
	v_fma_f32 v121, v121, v140, v155
	v_lshlrev_b32_e32 v153, 16, v177
	v_bfe_i32 v154, v222, 24, 4
	v_and_b32_e32 v155, 0xffff0000, v177
	v_bfe_i32 v156, v222, 28, 4
	v_lshl_add_u32 v153, v154, 12, v153
	v_lshl_add_u32 v155, v156, 12, v155
	v_fma_f32 v122, v122, v140, v153
	v_fma_f32 v123, v123, v140, v155
	global_store_dwordx4 v151, v[124:127], s[14:15] offset:0
	s_waitcnt vmcnt(25)
	v_lshlrev_b32_e32 v153, 16, v178
	v_bfe_i32 v154, v223, 0, 4
	v_and_b32_e32 v155, 0xffff0000, v178
	v_bfe_i32 v156, v223, 4, 4
	v_lshl_add_u32 v153, v154, 12, v153
	v_lshl_add_u32 v155, v156, 12, v155
	v_fma_f32 v116, v116, v140, v153
	v_fma_f32 v117, v117, v140, v155
	v_lshlrev_b32_e32 v153, 16, v179
	v_bfe_i32 v154, v223, 8, 4
	v_and_b32_e32 v155, 0xffff0000, v179
	v_bfe_i32 v156, v223, 12, 4
	v_lshl_add_u32 v153, v154, 12, v153
	v_lshl_add_u32 v155, v156, 12, v155
	v_fma_f32 v118, v118, v140, v153
	v_fma_f32 v119, v119, v140, v155
	global_store_dwordx4 v151, v[120:123], s[14:15] offset:16
	v_lshlrev_b32_e32 v153, 16, v180
	v_bfe_i32 v154, v223, 16, 4
	v_and_b32_e32 v155, 0xffff0000, v180
	v_bfe_i32 v156, v223, 20, 4
	v_lshl_add_u32 v153, v154, 12, v153
	v_lshl_add_u32 v155, v156, 12, v155
	v_fma_f32 v112, v112, v140, v153
	v_fma_f32 v113, v113, v140, v155
	v_lshlrev_b32_e32 v153, 16, v181
	v_bfe_i32 v154, v223, 24, 4
	v_and_b32_e32 v155, 0xffff0000, v181
	v_bfe_i32 v156, v223, 28, 4
	v_lshl_add_u32 v153, v154, 12, v153
	v_lshl_add_u32 v155, v156, 12, v155
	v_fma_f32 v114, v114, v140, v153
	v_fma_f32 v115, v115, v140, v155
	global_store_dwordx4 v151, v[116:119], s[14:15] offset:512
	global_store_dwordx4 v151, v[112:115], s[14:15] offset:528
	v_add_u32_e32 v151, 0x10000, v151
	s_waitcnt vmcnt(26)
	v_lshlrev_b32_e32 v153, 16, v182
	v_bfe_i32 v154, v224, 0, 4
	v_and_b32_e32 v155, 0xffff0000, v182
	v_bfe_i32 v156, v224, 4, 4
	v_lshl_add_u32 v153, v154, 12, v153
	v_lshl_add_u32 v155, v156, 12, v155
	v_fma_f32 v108, v108, v140, v153
	v_fma_f32 v109, v109, v140, v155
	v_lshlrev_b32_e32 v153, 16, v183
	v_bfe_i32 v154, v224, 8, 4
	v_and_b32_e32 v155, 0xffff0000, v183
	v_bfe_i32 v156, v224, 12, 4
	v_lshl_add_u32 v153, v154, 12, v153
	v_lshl_add_u32 v155, v156, 12, v155
	v_fma_f32 v110, v110, v140, v153
	v_fma_f32 v111, v111, v140, v155
	v_lshlrev_b32_e32 v153, 16, v184
	v_bfe_i32 v154, v224, 16, 4
	v_and_b32_e32 v155, 0xffff0000, v184
	v_bfe_i32 v156, v224, 20, 4
	v_lshl_add_u32 v153, v154, 12, v153
	v_lshl_add_u32 v155, v156, 12, v155
	v_fma_f32 v104, v104, v140, v153
	v_fma_f32 v105, v105, v140, v155
	v_lshlrev_b32_e32 v153, 16, v185
	v_bfe_i32 v154, v224, 24, 4
	v_and_b32_e32 v155, 0xffff0000, v185
	v_bfe_i32 v156, v224, 28, 4
	v_lshl_add_u32 v153, v154, 12, v153
	v_lshl_add_u32 v155, v156, 12, v155
	v_fma_f32 v106, v106, v140, v153
	v_fma_f32 v107, v107, v140, v155
	global_store_dwordx4 v151, v[108:111], s[14:15] offset:0
	s_waitcnt vmcnt(25)
	v_lshlrev_b32_e32 v153, 16, v186
	v_bfe_i32 v154, v225, 0, 4
	v_and_b32_e32 v155, 0xffff0000, v186
	v_bfe_i32 v156, v225, 4, 4
	v_lshl_add_u32 v153, v154, 12, v153
	v_lshl_add_u32 v155, v156, 12, v155
	v_fma_f32 v100, v100, v140, v153
	v_fma_f32 v101, v101, v140, v155
	v_lshlrev_b32_e32 v153, 16, v187
	v_bfe_i32 v154, v225, 8, 4
	v_and_b32_e32 v155, 0xffff0000, v187
	v_bfe_i32 v156, v225, 12, 4
	v_lshl_add_u32 v153, v154, 12, v153
	v_lshl_add_u32 v155, v156, 12, v155
	v_fma_f32 v102, v102, v140, v153
	v_fma_f32 v103, v103, v140, v155
	global_store_dwordx4 v151, v[104:107], s[14:15] offset:16
	v_lshlrev_b32_e32 v153, 16, v188
	v_bfe_i32 v154, v225, 16, 4
	v_and_b32_e32 v155, 0xffff0000, v188
	v_bfe_i32 v156, v225, 20, 4
	v_lshl_add_u32 v153, v154, 12, v153
	v_lshl_add_u32 v155, v156, 12, v155
	v_fma_f32 v96, v96, v140, v153
	v_fma_f32 v97, v97, v140, v155
	v_lshlrev_b32_e32 v153, 16, v189
	v_bfe_i32 v154, v225, 24, 4
	v_and_b32_e32 v155, 0xffff0000, v189
	v_bfe_i32 v156, v225, 28, 4
	v_lshl_add_u32 v153, v154, 12, v153
	v_lshl_add_u32 v155, v156, 12, v155
	v_fma_f32 v98, v98, v140, v153
	v_fma_f32 v99, v99, v140, v155
	global_store_dwordx4 v151, v[100:103], s[14:15] offset:512
	global_store_dwordx4 v151, v[96:99], s[14:15] offset:528
	v_add_u32_e32 v151, 0x10000, v151
	s_nop 1
	global_load_dwordx4 v[174:177], v150, s[34:35] offset:0
	global_load_dwordx4 v[178:181], v150, s[34:35] offset:256
	v_add_u32_e32 v150, 0x8000, v150
	global_load_dwordx4 v[182:185], v150, s[34:35] offset:0
	global_load_dwordx4 v[186:189], v150, s[34:35] offset:256
	s_waitcnt vmcnt(30)
	v_lshlrev_b32_e32 v153, 16, v190
	v_bfe_i32 v154, v226, 0, 4
	v_and_b32_e32 v155, 0xffff0000, v190
	v_bfe_i32 v156, v226, 4, 4
	v_lshl_add_u32 v153, v154, 12, v153
	v_lshl_add_u32 v155, v156, 12, v155
	v_fma_f32 v92, v92, v140, v153
	v_fma_f32 v93, v93, v140, v155
	v_lshlrev_b32_e32 v153, 16, v191
	v_bfe_i32 v154, v226, 8, 4
	v_and_b32_e32 v155, 0xffff0000, v191
	v_bfe_i32 v156, v226, 12, 4
	v_lshl_add_u32 v153, v154, 12, v153
	v_lshl_add_u32 v155, v156, 12, v155
	v_fma_f32 v94, v94, v140, v153
	v_fma_f32 v95, v95, v140, v155
	v_lshlrev_b32_e32 v153, 16, v192
	v_bfe_i32 v154, v226, 16, 4
	v_and_b32_e32 v155, 0xffff0000, v192
	v_bfe_i32 v156, v226, 20, 4
	v_lshl_add_u32 v153, v154, 12, v153
	v_lshl_add_u32 v155, v156, 12, v155
	v_fma_f32 v88, v88, v140, v153
	v_fma_f32 v89, v89, v140, v155
	v_lshlrev_b32_e32 v153, 16, v193
	v_bfe_i32 v154, v226, 24, 4
	v_and_b32_e32 v155, 0xffff0000, v193
	v_bfe_i32 v156, v226, 28, 4
	v_lshl_add_u32 v153, v154, 12, v153
	v_lshl_add_u32 v155, v156, 12, v155
	v_fma_f32 v90, v90, v140, v153
	v_fma_f32 v91, v91, v140, v155
	global_store_dwordx4 v151, v[92:95], s[14:15] offset:0
	s_waitcnt vmcnt(29)
	v_lshlrev_b32_e32 v153, 16, v194
	v_bfe_i32 v154, v227, 0, 4
	v_and_b32_e32 v155, 0xffff0000, v194
	v_bfe_i32 v156, v227, 4, 4
	v_lshl_add_u32 v153, v154, 12, v153
	v_lshl_add_u32 v155, v156, 12, v155
	v_fma_f32 v84, v84, v140, v153
	v_fma_f32 v85, v85, v140, v155
	v_lshlrev_b32_e32 v153, 16, v195
	v_bfe_i32 v154, v227, 8, 4
	v_and_b32_e32 v155, 0xffff0000, v195
	v_bfe_i32 v156, v227, 12, 4
	v_lshl_add_u32 v153, v154, 12, v153
	v_lshl_add_u32 v155, v156, 12, v155
	v_fma_f32 v86, v86, v140, v153
	v_fma_f32 v87, v87, v140, v155
	global_store_dwordx4 v151, v[88:91], s[14:15] offset:16
	v_lshlrev_b32_e32 v153, 16, v196
	v_bfe_i32 v154, v227, 16, 4
	v_and_b32_e32 v155, 0xffff0000, v196
	v_bfe_i32 v156, v227, 20, 4
	v_lshl_add_u32 v153, v154, 12, v153
	v_lshl_add_u32 v155, v156, 12, v155
	v_fma_f32 v80, v80, v140, v153
	v_fma_f32 v81, v81, v140, v155
	v_lshlrev_b32_e32 v153, 16, v197
	v_bfe_i32 v154, v227, 24, 4
	v_and_b32_e32 v155, 0xffff0000, v197
	v_bfe_i32 v156, v227, 28, 4
	v_lshl_add_u32 v153, v154, 12, v153
	v_lshl_add_u32 v155, v156, 12, v155
	v_fma_f32 v82, v82, v140, v153
	v_fma_f32 v83, v83, v140, v155
	global_store_dwordx4 v151, v[84:87], s[14:15] offset:512
	global_store_dwordx4 v151, v[80:83], s[14:15] offset:528
	v_add_u32_e32 v151, 0x10000, v151
	s_waitcnt vmcnt(30)
	v_lshlrev_b32_e32 v153, 16, v198
	v_bfe_i32 v154, v228, 0, 4
	v_and_b32_e32 v155, 0xffff0000, v198
	v_bfe_i32 v156, v228, 4, 4
	v_lshl_add_u32 v153, v154, 12, v153
	v_lshl_add_u32 v155, v156, 12, v155
	v_fma_f32 v76, v76, v140, v153
	v_fma_f32 v77, v77, v140, v155
	v_lshlrev_b32_e32 v153, 16, v199
	v_bfe_i32 v154, v228, 8, 4
	v_and_b32_e32 v155, 0xffff0000, v199
	v_bfe_i32 v156, v228, 12, 4
	v_lshl_add_u32 v153, v154, 12, v153
	v_lshl_add_u32 v155, v156, 12, v155
	v_fma_f32 v78, v78, v140, v153
	v_fma_f32 v79, v79, v140, v155
	v_lshlrev_b32_e32 v153, 16, v200
	v_bfe_i32 v154, v228, 16, 4
	v_and_b32_e32 v155, 0xffff0000, v200
	v_bfe_i32 v156, v228, 20, 4
	v_lshl_add_u32 v153, v154, 12, v153
	v_lshl_add_u32 v155, v156, 12, v155
	v_fma_f32 v72, v72, v140, v153
	v_fma_f32 v73, v73, v140, v155
	v_lshlrev_b32_e32 v153, 16, v201
	v_bfe_i32 v154, v228, 24, 4
	v_and_b32_e32 v155, 0xffff0000, v201
	v_bfe_i32 v156, v228, 28, 4
	v_lshl_add_u32 v153, v154, 12, v153
	v_lshl_add_u32 v155, v156, 12, v155
	v_fma_f32 v74, v74, v140, v153
	v_fma_f32 v75, v75, v140, v155
	global_store_dwordx4 v151, v[76:79], s[14:15] offset:0
	s_waitcnt vmcnt(29)
	v_lshlrev_b32_e32 v153, 16, v202
	v_bfe_i32 v154, v229, 0, 4
	v_and_b32_e32 v155, 0xffff0000, v202
	v_bfe_i32 v156, v229, 4, 4
	v_lshl_add_u32 v153, v154, 12, v153
	v_lshl_add_u32 v155, v156, 12, v155
	v_fma_f32 v68, v68, v140, v153
	v_fma_f32 v69, v69, v140, v155
	v_lshlrev_b32_e32 v153, 16, v203
	v_bfe_i32 v154, v229, 8, 4
	v_and_b32_e32 v155, 0xffff0000, v203
	v_bfe_i32 v156, v229, 12, 4
	v_lshl_add_u32 v153, v154, 12, v153
	v_lshl_add_u32 v155, v156, 12, v155
	v_fma_f32 v70, v70, v140, v153
	v_fma_f32 v71, v71, v140, v155
	global_store_dwordx4 v151, v[72:75], s[14:15] offset:16
	v_lshlrev_b32_e32 v153, 16, v204
	v_bfe_i32 v154, v229, 16, 4
	v_and_b32_e32 v155, 0xffff0000, v204
	v_bfe_i32 v156, v229, 20, 4
	v_lshl_add_u32 v153, v154, 12, v153
	v_lshl_add_u32 v155, v156, 12, v155
	v_fma_f32 v64, v64, v140, v153
	v_fma_f32 v65, v65, v140, v155
	v_lshlrev_b32_e32 v153, 16, v205
	v_bfe_i32 v154, v229, 24, 4
	v_and_b32_e32 v155, 0xffff0000, v205
	v_bfe_i32 v156, v229, 28, 4
	v_lshl_add_u32 v153, v154, 12, v153
	v_lshl_add_u32 v155, v156, 12, v155
	v_fma_f32 v66, v66, v140, v153
	v_fma_f32 v67, v67, v140, v155
	global_store_dwordx4 v151, v[68:71], s[14:15] offset:512
	global_store_dwordx4 v151, v[64:67], s[14:15] offset:528
	v_add_u32_e32 v151, 0x50000, v151
	s_waitcnt vmcnt(30)
	v_lshlrev_b32_e32 v153, 16, v206
	v_bfe_i32 v154, v230, 0, 4
	v_and_b32_e32 v155, 0xffff0000, v206
	v_bfe_i32 v156, v230, 4, 4
	v_lshl_add_u32 v153, v154, 12, v153
	v_lshl_add_u32 v155, v156, 12, v155
	v_fma_f32 v60, v60, v140, v153
	v_fma_f32 v61, v61, v140, v155
	v_lshlrev_b32_e32 v153, 16, v207
	v_bfe_i32 v154, v230, 8, 4
	v_and_b32_e32 v155, 0xffff0000, v207
	v_bfe_i32 v156, v230, 12, 4
	v_lshl_add_u32 v153, v154, 12, v153
	v_lshl_add_u32 v155, v156, 12, v155
	v_fma_f32 v62, v62, v140, v153
	v_fma_f32 v63, v63, v140, v155
	v_lshlrev_b32_e32 v153, 16, v208
	v_bfe_i32 v154, v230, 16, 4
	v_and_b32_e32 v155, 0xffff0000, v208
	v_bfe_i32 v156, v230, 20, 4
	v_lshl_add_u32 v153, v154, 12, v153
	v_lshl_add_u32 v155, v156, 12, v155
	v_fma_f32 v56, v56, v140, v153
	v_fma_f32 v57, v57, v140, v155
	v_lshlrev_b32_e32 v153, 16, v209
	v_bfe_i32 v154, v230, 24, 4
	v_and_b32_e32 v155, 0xffff0000, v209
	v_bfe_i32 v156, v230, 28, 4
	v_lshl_add_u32 v153, v154, 12, v153
	v_lshl_add_u32 v155, v156, 12, v155
	v_fma_f32 v58, v58, v140, v153
	v_fma_f32 v59, v59, v140, v155
	global_store_dwordx4 v151, v[60:63], s[14:15] offset:0
	s_waitcnt vmcnt(29)
	v_lshlrev_b32_e32 v153, 16, v210
	v_bfe_i32 v154, v231, 0, 4
	v_and_b32_e32 v155, 0xffff0000, v210
	v_bfe_i32 v156, v231, 4, 4
	v_lshl_add_u32 v153, v154, 12, v153
	v_lshl_add_u32 v155, v156, 12, v155
	v_fma_f32 v52, v52, v140, v153
	v_fma_f32 v53, v53, v140, v155
	v_lshlrev_b32_e32 v153, 16, v211
	v_bfe_i32 v154, v231, 8, 4
	v_and_b32_e32 v155, 0xffff0000, v211
	v_bfe_i32 v156, v231, 12, 4
	v_lshl_add_u32 v153, v154, 12, v153
	v_lshl_add_u32 v155, v156, 12, v155
	v_fma_f32 v54, v54, v140, v153
	v_fma_f32 v55, v55, v140, v155
	global_store_dwordx4 v151, v[56:59], s[14:15] offset:16
	v_lshlrev_b32_e32 v153, 16, v212
	v_bfe_i32 v154, v231, 16, 4
	v_and_b32_e32 v155, 0xffff0000, v212
	v_bfe_i32 v156, v231, 20, 4
	v_lshl_add_u32 v153, v154, 12, v153
	v_lshl_add_u32 v155, v156, 12, v155
	v_fma_f32 v48, v48, v140, v153
	v_fma_f32 v49, v49, v140, v155
	v_lshlrev_b32_e32 v153, 16, v213
	v_bfe_i32 v154, v231, 24, 4
	v_and_b32_e32 v155, 0xffff0000, v213
	v_bfe_i32 v156, v231, 28, 4
	v_lshl_add_u32 v153, v154, 12, v153
	v_lshl_add_u32 v155, v156, 12, v155
	v_fma_f32 v50, v50, v140, v153
	v_fma_f32 v51, v51, v140, v155
	global_store_dwordx4 v151, v[52:55], s[14:15] offset:512
	global_store_dwordx4 v151, v[48:51], s[14:15] offset:528
	v_add_u32_e32 v151, 0x10000, v151
	s_waitcnt vmcnt(30)
	v_lshlrev_b32_e32 v153, 16, v214
	v_bfe_i32 v154, v232, 0, 4
	v_and_b32_e32 v155, 0xffff0000, v214
	v_bfe_i32 v156, v232, 4, 4
	v_lshl_add_u32 v153, v154, 12, v153
	v_lshl_add_u32 v155, v156, 12, v155
	v_fma_f32 v44, v44, v140, v153
	v_fma_f32 v45, v45, v140, v155
	v_lshlrev_b32_e32 v153, 16, v215
	v_bfe_i32 v154, v232, 8, 4
	v_and_b32_e32 v155, 0xffff0000, v215
	v_bfe_i32 v156, v232, 12, 4
	v_lshl_add_u32 v153, v154, 12, v153
	v_lshl_add_u32 v155, v156, 12, v155
	v_fma_f32 v46, v46, v140, v153
	v_fma_f32 v47, v47, v140, v155
	v_lshlrev_b32_e32 v153, 16, v216
	v_bfe_i32 v154, v232, 16, 4
	v_and_b32_e32 v155, 0xffff0000, v216
	v_bfe_i32 v156, v232, 20, 4
	v_lshl_add_u32 v153, v154, 12, v153
	v_lshl_add_u32 v155, v156, 12, v155
	v_fma_f32 v40, v40, v140, v153
	v_fma_f32 v41, v41, v140, v155
	v_lshlrev_b32_e32 v153, 16, v217
	v_bfe_i32 v154, v232, 24, 4
	v_and_b32_e32 v155, 0xffff0000, v217
	v_bfe_i32 v156, v232, 28, 4
	v_lshl_add_u32 v153, v154, 12, v153
	v_lshl_add_u32 v155, v156, 12, v155
	v_fma_f32 v42, v42, v140, v153
	v_fma_f32 v43, v43, v140, v155
	global_store_dwordx4 v151, v[44:47], s[14:15] offset:0
	s_waitcnt vmcnt(29)
	v_lshlrev_b32_e32 v153, 16, v218
	v_bfe_i32 v154, v233, 0, 4
	v_and_b32_e32 v155, 0xffff0000, v218
	v_bfe_i32 v156, v233, 4, 4
	v_lshl_add_u32 v153, v154, 12, v153
	v_lshl_add_u32 v155, v156, 12, v155
	v_fma_f32 v36, v36, v140, v153
	v_fma_f32 v37, v37, v140, v155
	v_lshlrev_b32_e32 v153, 16, v219
	v_bfe_i32 v154, v233, 8, 4
	v_and_b32_e32 v155, 0xffff0000, v219
	v_bfe_i32 v156, v233, 12, 4
	v_lshl_add_u32 v153, v154, 12, v153
	v_lshl_add_u32 v155, v156, 12, v155
	v_fma_f32 v38, v38, v140, v153
	v_fma_f32 v39, v39, v140, v155
	global_store_dwordx4 v151, v[40:43], s[14:15] offset:16
	v_lshlrev_b32_e32 v153, 16, v220
	v_bfe_i32 v154, v233, 16, 4
	v_and_b32_e32 v155, 0xffff0000, v220
	v_bfe_i32 v156, v233, 20, 4
	v_lshl_add_u32 v153, v154, 12, v153
	v_lshl_add_u32 v155, v156, 12, v155
	v_fma_f32 v32, v32, v140, v153
	v_fma_f32 v33, v33, v140, v155
	v_lshlrev_b32_e32 v153, 16, v221
	v_bfe_i32 v154, v233, 24, 4
	v_and_b32_e32 v155, 0xffff0000, v221
	v_bfe_i32 v156, v233, 28, 4
	v_lshl_add_u32 v153, v154, 12, v153
	v_lshl_add_u32 v155, v156, 12, v155
	v_fma_f32 v34, v34, v140, v153
	v_fma_f32 v35, v35, v140, v155
	global_store_dwordx4 v151, v[36:39], s[14:15] offset:512
	global_store_dwordx4 v151, v[32:35], s[14:15] offset:528
	v_add_u32_e32 v151, 0x10000, v151
	s_waitcnt vmcnt(19)
	v_lshlrev_b32_e32 v153, 16, v174
	v_bfe_i32 v154, v234, 0, 4
	v_and_b32_e32 v155, 0xffff0000, v174
	v_bfe_i32 v156, v234, 4, 4
	v_lshl_add_u32 v153, v154, 12, v153
	v_lshl_add_u32 v155, v156, 12, v155
	v_fma_f32 v28, v28, v140, v153
	v_fma_f32 v29, v29, v140, v155
	v_lshlrev_b32_e32 v153, 16, v175
	v_bfe_i32 v154, v234, 8, 4
	v_and_b32_e32 v155, 0xffff0000, v175
	v_bfe_i32 v156, v234, 12, 4
	v_lshl_add_u32 v153, v154, 12, v153
	v_lshl_add_u32 v155, v156, 12, v155
	v_fma_f32 v30, v30, v140, v153
	v_fma_f32 v31, v31, v140, v155
	v_lshlrev_b32_e32 v153, 16, v176
	v_bfe_i32 v154, v234, 16, 4
	v_and_b32_e32 v155, 0xffff0000, v176
	v_bfe_i32 v156, v234, 20, 4
	v_lshl_add_u32 v153, v154, 12, v153
	v_lshl_add_u32 v155, v156, 12, v155
	v_fma_f32 v24, v24, v140, v153
	v_fma_f32 v25, v25, v140, v155
	v_lshlrev_b32_e32 v153, 16, v177
	v_bfe_i32 v154, v234, 24, 4
	v_and_b32_e32 v155, 0xffff0000, v177
	v_bfe_i32 v156, v234, 28, 4
	v_lshl_add_u32 v153, v154, 12, v153
	v_lshl_add_u32 v155, v156, 12, v155
	v_fma_f32 v26, v26, v140, v153
	v_fma_f32 v27, v27, v140, v155
	global_store_dwordx4 v151, v[28:31], s[14:15] offset:0
	s_waitcnt vmcnt(19)
	v_lshlrev_b32_e32 v153, 16, v178
	v_bfe_i32 v154, v235, 0, 4
	v_and_b32_e32 v155, 0xffff0000, v178
	v_bfe_i32 v156, v235, 4, 4
	v_lshl_add_u32 v153, v154, 12, v153
	v_lshl_add_u32 v155, v156, 12, v155
	v_fma_f32 v20, v20, v140, v153
	v_fma_f32 v21, v21, v140, v155
	v_lshlrev_b32_e32 v153, 16, v179
	v_bfe_i32 v154, v235, 8, 4
	v_and_b32_e32 v155, 0xffff0000, v179
	v_bfe_i32 v156, v235, 12, 4
	v_lshl_add_u32 v153, v154, 12, v153
	v_lshl_add_u32 v155, v156, 12, v155
	v_fma_f32 v22, v22, v140, v153
	v_fma_f32 v23, v23, v140, v155
	global_store_dwordx4 v151, v[24:27], s[14:15] offset:16
	v_lshlrev_b32_e32 v153, 16, v180
	v_bfe_i32 v154, v235, 16, 4
	v_and_b32_e32 v155, 0xffff0000, v180
	v_bfe_i32 v156, v235, 20, 4
	v_lshl_add_u32 v153, v154, 12, v153
	v_lshl_add_u32 v155, v156, 12, v155
	v_fma_f32 v16, v16, v140, v153
	v_fma_f32 v17, v17, v140, v155
	v_lshlrev_b32_e32 v153, 16, v181
	v_bfe_i32 v154, v235, 24, 4
	v_and_b32_e32 v155, 0xffff0000, v181
	v_bfe_i32 v156, v235, 28, 4
	v_lshl_add_u32 v153, v154, 12, v153
	v_lshl_add_u32 v155, v156, 12, v155
	v_fma_f32 v18, v18, v140, v153
	v_fma_f32 v19, v19, v140, v155
	global_store_dwordx4 v151, v[20:23], s[14:15] offset:512
	global_store_dwordx4 v151, v[16:19], s[14:15] offset:528
	v_add_u32_e32 v151, 0x10000, v151
	s_waitcnt vmcnt(21)
	v_lshlrev_b32_e32 v153, 16, v182
	v_bfe_i32 v154, v236, 0, 4
	v_and_b32_e32 v155, 0xffff0000, v182
	v_bfe_i32 v156, v236, 4, 4
	v_lshl_add_u32 v153, v154, 12, v153
	v_lshl_add_u32 v155, v156, 12, v155
	v_fma_f32 v12, v12, v140, v153
	v_fma_f32 v13, v13, v140, v155
	v_lshlrev_b32_e32 v153, 16, v183
	v_bfe_i32 v154, v236, 8, 4
	v_and_b32_e32 v155, 0xffff0000, v183
	v_bfe_i32 v156, v236, 12, 4
	v_lshl_add_u32 v153, v154, 12, v153
	v_lshl_add_u32 v155, v156, 12, v155
	v_fma_f32 v14, v14, v140, v153
	v_fma_f32 v15, v15, v140, v155
	v_lshlrev_b32_e32 v153, 16, v184
	v_bfe_i32 v154, v236, 16, 4
	v_and_b32_e32 v155, 0xffff0000, v184
	v_bfe_i32 v156, v236, 20, 4
	v_lshl_add_u32 v153, v154, 12, v153
	v_lshl_add_u32 v155, v156, 12, v155
	v_fma_f32 v8, v8, v140, v153
	v_fma_f32 v9, v9, v140, v155
	v_lshlrev_b32_e32 v153, 16, v185
	v_bfe_i32 v154, v236, 24, 4
	v_and_b32_e32 v155, 0xffff0000, v185
	v_bfe_i32 v156, v236, 28, 4
	v_lshl_add_u32 v153, v154, 12, v153
	v_lshl_add_u32 v155, v156, 12, v155
	v_fma_f32 v10, v10, v140, v153
	v_fma_f32 v11, v11, v140, v155
	global_store_dwordx4 v151, v[12:15], s[14:15] offset:0
	s_waitcnt vmcnt(21)
	v_lshlrev_b32_e32 v153, 16, v186
	v_bfe_i32 v154, v237, 0, 4
	v_and_b32_e32 v155, 0xffff0000, v186
	v_bfe_i32 v156, v237, 4, 4
	v_lshl_add_u32 v153, v154, 12, v153
	v_lshl_add_u32 v155, v156, 12, v155
	v_fma_f32 v0, v0, v140, v153
	v_fma_f32 v1, v1, v140, v155
	v_lshlrev_b32_e32 v153, 16, v187
	v_bfe_i32 v154, v237, 8, 4
	v_and_b32_e32 v155, 0xffff0000, v187
	v_bfe_i32 v156, v237, 12, 4
	v_lshl_add_u32 v153, v154, 12, v153
	v_lshl_add_u32 v155, v156, 12, v155
	v_fma_f32 v2, v2, v140, v153
	v_fma_f32 v3, v3, v140, v155
	global_store_dwordx4 v151, v[8:11], s[14:15] offset:16
	v_lshlrev_b32_e32 v153, 16, v188
	v_bfe_i32 v154, v237, 16, 4
	v_and_b32_e32 v155, 0xffff0000, v188
	v_bfe_i32 v156, v237, 20, 4
	v_lshl_add_u32 v153, v154, 12, v153
	v_lshl_add_u32 v155, v156, 12, v155
	v_fma_f32 v4, v4, v140, v153
	v_fma_f32 v5, v5, v140, v155
	v_lshlrev_b32_e32 v153, 16, v189
	v_bfe_i32 v154, v237, 24, 4
	v_and_b32_e32 v155, 0xffff0000, v189
	v_bfe_i32 v156, v237, 28, 4
	v_lshl_add_u32 v153, v154, 12, v153
	v_lshl_add_u32 v155, v156, 12, v155
	v_fma_f32 v6, v6, v140, v153
	v_fma_f32 v7, v7, v140, v155
	global_store_dwordx4 v151, v[0:3], s[14:15] offset:512
	global_store_dwordx4 v151, v[4:7], s[14:15] offset:528
